# plus packed-f32 SSD conv, dwordx4 epilogue stores via permlane16_swap (INPROJ, OUTPROJ, RES), batched RES accumulator-init loads
# speedup vs baseline: 1.0253x; 1.0253x over previous
; #define PG8_STAGE(bufoff, gbase) do { _Pragma("unroll") for (int _i = 0; _i < 2; ++_i) \
;     __builtin_amdgcn_global_load_lds((const unsigned*)((const char*)(gbase) + voff[_i]), (LAS unsigned*)(lds + (bufoff) + ldsw + _i * 8192), 16, 0, 0); } while (0)
; #define PG8_LDA(dst, b, h) do { _Pragma("unroll") for (int m = 0; m < 4; ++m) _Pragma("unroll") for (int k = 0; k < 2; ++k) dst[m][k] = *(const LAS bf16x8*)(lds + PG8_SA(b, h) + aoff + m * 2048 + k * 1024); } while (0)
; #define PG8_LDB(dst, b, h) do { _Pragma("unroll") for (int n = 0; n < 2; ++n) _Pragma("unroll") for (int k = 0; k < 2; ++k) dst[n][k] = *(const LAS bf16x8*)(lds + PG8_SB(b, h) + boff + n * 2048 + k * 1024); } while (0)
; #define PG8_MMA(ai, bj, At, Bt_) do { __builtin_amdgcn_s_setprio(1); _Pragma("unroll") for (int m = 0; m < 4; ++m) _Pragma("unroll") for (int n = 0; n < 2; ++n) _Pragma("unroll") for (int k = 0; k < 2; ++k) \
;     acc[ai][bj][m][n] = __builtin_amdgcn_mfma_f32_16x16x32_bf16(Bt_[n][k], At[m][k], acc[ai][bj][m][n], 0, 0, 0); __builtin_amdgcn_s_setprio(0); } while (0)
; #define PG8_WAIT_L(n) asm volatile("s_waitcnt lgkmcnt(" #n ")" ::: "memory")
; #define PG8_BAR __builtin_amdgcn_s_barrier()
; #define PG8_SCHED __builtin_amdgcn_sched_barrier(0)
; template <int EPI>
; __device__ __forceinline__ void gemm_phase(KP P, const bfu* __restrict__ A, const bfu* __restrict__ Bt, int K, int ntn, char* smem, const int wv) {
;     ...
;     for (int t = 0; t < nt; t += 2) {
;       const bool last = (t == nt - 2);
;       const char* a1 = cA + (size_t)(t + 1) * kstep;
;       const char* a2 = last ? nA : cA + (size_t)(t + 2) * kstep;
;       const char* b2 = last ? nB : cB + (size_t)(t + 2) * kstep;
;       const char* a3 = a2 + kstep;
;       const char* b3 = b2 + kstep;
;       PG8_LDB(B0, 0, 0); PG8_SCHED; PG8_LDA(At, 0, 0); PG8_STAGE(PG8_SA(1, 1), a1 + hstep);
;       PG8_WAIT_L(8); PG8_BAR; PG8_WAIT_L(0); PG8_MMA(0, 0, At, B0); PG8_BAR; PG8_SCHED;
;       PG8_LDB(B1, 0, 1); PG8_STAGE(PG8_SB(0, 0), b2);
;       PG8_BAR; PG8_WAIT_L(0); PG8_MMA(0, 1, At, B1); PG8_BAR;
;       PG8_LDA(At, 0, 1); PG8_STAGE(PG8_SA(0, 0), a2);
;       PG8_BAR; PG8_WAIT_L(0); PG8_MMA(1, 0, At, B0); PG8_BAR; PG8_SCHED;
.LBB0_283:
	v_add_u32_e32 v0, s35, v142
	ds_read_b128 v[150:153], v0
	ds_read_b128 v[154:157], v0 offset:1024
	ds_read_b128 v[158:161], v0 offset:2048
	ds_read_b128 v[180:183], v0 offset:3072
	s_add_i32 s82, s18, 2
	s_add_u32 s22, s20, 0x80
	s_addc_u32 s19, s21, 0
	s_cmp_eq_u32 s67, s18
	s_cselect_b32 s18, s10, s22
	s_cselect_b32 s19, s11, s19
	s_cselect_b32 s23, s79, s81
	s_cselect_b32 s22, s78, s80
	v_lshl_add_u64 v[144:145], s[20:21], 0, v[136:137]
	s_add_i32 m0, s38, 0xc000
	ds_read_b128 v[184:187], v143
	ds_read_b128 v[188:191], v143 offset:1024
	ds_read_b128 v[192:195], v143 offset:2048
	ds_read_b128 v[196:199], v143 offset:3072
	ds_read_b128 v[200:203], v143 offset:4096
	ds_read_b128 v[204:207], v143 offset:5120
	ds_read_b128 v[208:211], v143 offset:6144
	ds_read_b128 v[212:215], v143 offset:7168
	global_load_lds_dwordx4 v[144:145], off
	v_lshl_add_u64 v[144:145], s[20:21], 0, v[138:139]
	s_add_i32 m0, s38, 0xe000
	s_nop 0
	global_load_lds_dwordx4 v[144:145], off
	s_waitcnt lgkmcnt(8)
	s_barrier
	s_waitcnt lgkmcnt(0)
	s_setprio 1
	s_waitcnt lgkmcnt(0)
	v_mfma_f32_16x16x32_bf16 v[2:5], v[150:153], v[184:187], v[2:5]
	v_mfma_f32_16x16x32_bf16 v[6:9], v[158:161], v[184:187], v[6:9]
	v_mfma_f32_16x16x32_bf16 v[10:13], v[150:153], v[192:195], v[10:13]
	v_mfma_f32_16x16x32_bf16 v[14:17], v[158:161], v[192:195], v[14:17]
	v_mfma_f32_16x16x32_bf16 v[26:29], v[150:153], v[200:203], v[26:29]
	v_mfma_f32_16x16x32_bf16 v[30:33], v[158:161], v[200:203], v[30:33]
	v_mfma_f32_16x16x32_bf16 v[42:45], v[150:153], v[208:211], v[42:45]
	v_mfma_f32_16x16x32_bf16 v[46:49], v[158:161], v[208:211], v[46:49]
	v_mfma_f32_16x16x32_bf16 v[2:5], v[154:157], v[188:191], v[2:5]
	v_mfma_f32_16x16x32_bf16 v[6:9], v[180:183], v[188:191], v[6:9]
	v_mfma_f32_16x16x32_bf16 v[10:13], v[154:157], v[196:199], v[10:13]
	v_mfma_f32_16x16x32_bf16 v[14:17], v[180:183], v[196:199], v[14:17]
	v_mfma_f32_16x16x32_bf16 v[26:29], v[154:157], v[204:207], v[26:29]
	v_mfma_f32_16x16x32_bf16 v[30:33], v[180:183], v[204:207], v[30:33]
	v_mfma_f32_16x16x32_bf16 v[42:45], v[154:157], v[212:215], v[42:45]
	v_mfma_f32_16x16x32_bf16 v[46:49], v[180:183], v[212:215], v[46:49]
	s_setprio 0
	s_barrier
	s_mov_b32 m0, s36
	v_add_u32_e32 v0, s40, v142
	v_lshl_add_u64 v[144:145], s[22:23], 0, v[130:131]
	ds_read_b128 v[216:219], v0
	ds_read_b128 v[220:223], v0 offset:1024
	ds_read_b128 v[224:227], v0 offset:2048
	ds_read_b128 v[228:231], v0 offset:3072
	global_load_lds_dwordx4 v[144:145], off
	v_lshl_add_u64 v[162:163], s[22:23], 0, v[132:133]
	s_mov_b32 m0, s37
	s_nop 0
	global_load_lds_dwordx4 v[162:163], off
	s_barrier
	s_waitcnt lgkmcnt(0)
	s_setprio 1
	s_waitcnt lgkmcnt(0)
	v_mfma_f32_16x16x32_bf16 v[18:21], v[216:219], v[184:187], v[18:21]
	v_mfma_f32_16x16x32_bf16 v[22:25], v[224:227], v[184:187], v[22:25]
	v_mfma_f32_16x16x32_bf16 v[34:37], v[216:219], v[192:195], v[34:37]
	v_mfma_f32_16x16x32_bf16 v[38:41], v[224:227], v[192:195], v[38:41]
	v_mfma_f32_16x16x32_bf16 v[50:53], v[216:219], v[200:203], v[50:53]
	v_mfma_f32_16x16x32_bf16 v[54:57], v[224:227], v[200:203], v[54:57]
	v_mfma_f32_16x16x32_bf16 v[58:61], v[216:219], v[208:211], v[58:61]
	v_mfma_f32_16x16x32_bf16 v[62:65], v[224:227], v[208:211], v[62:65]
	v_mfma_f32_16x16x32_bf16 v[18:21], v[220:223], v[188:191], v[18:21]
	v_mfma_f32_16x16x32_bf16 v[22:25], v[228:231], v[188:191], v[22:25]
	v_mfma_f32_16x16x32_bf16 v[34:37], v[220:223], v[196:199], v[34:37]
	v_mfma_f32_16x16x32_bf16 v[38:41], v[228:231], v[196:199], v[38:41]
	v_mfma_f32_16x16x32_bf16 v[50:53], v[220:223], v[204:207], v[50:53]
	v_mfma_f32_16x16x32_bf16 v[54:57], v[228:231], v[204:207], v[54:57]
	v_mfma_f32_16x16x32_bf16 v[58:61], v[220:223], v[212:215], v[58:61]
	v_mfma_f32_16x16x32_bf16 v[62:65], v[228:231], v[212:215], v[62:65]
	s_setprio 0
	s_mov_b32 m0, s38
	v_lshl_add_u64 v[232:233], s[18:19], 0, v[130:131]
	s_barrier
	ds_read_b128 v[184:187], v143 offset:16384
	ds_read_b128 v[188:191], v143 offset:17408
	ds_read_b128 v[192:195], v143 offset:18432
	ds_read_b128 v[196:199], v143 offset:19456
	ds_read_b128 v[200:203], v143 offset:20480
	ds_read_b128 v[204:207], v143 offset:21504
	ds_read_b128 v[208:211], v143 offset:22528
	ds_read_b128 v[212:215], v143 offset:23552
	global_load_lds_dwordx4 v[232:233], off
	v_lshl_add_u64 v[234:235], s[18:19], 0, v[132:133]
	s_mov_b32 m0, s39
	s_nop 0
	global_load_lds_dwordx4 v[234:235], off
	s_barrier
	s_waitcnt lgkmcnt(0)
	s_setprio 1
	s_waitcnt lgkmcnt(0)
	v_mfma_f32_16x16x32_bf16 v[66:69], v[150:153], v[184:187], v[66:69]
	v_mfma_f32_16x16x32_bf16 v[70:73], v[158:161], v[184:187], v[70:73]
	v_mfma_f32_16x16x32_bf16 v[98:101], v[150:153], v[192:195], v[98:101]
	v_mfma_f32_16x16x32_bf16 v[102:105], v[158:161], v[192:195], v[102:105]
	v_mfma_f32_16x16x32_bf16 v[114:117], v[150:153], v[200:203], v[114:117]
	v_mfma_f32_16x16x32_bf16 v[118:121], v[158:161], v[200:203], v[118:121]
	v_mfma_f32_16x16x32_bf16 v[122:125], v[150:153], v[208:211], v[122:125]
	v_mfma_f32_16x16x32_bf16 v[126:129], v[158:161], v[208:211], v[126:129]
	v_mfma_f32_16x16x32_bf16 v[66:69], v[154:157], v[188:191], v[66:69]
	v_mfma_f32_16x16x32_bf16 v[70:73], v[180:183], v[188:191], v[70:73]
	v_mfma_f32_16x16x32_bf16 v[98:101], v[154:157], v[196:199], v[98:101]
	v_mfma_f32_16x16x32_bf16 v[102:105], v[180:183], v[196:199], v[102:105]
	v_mfma_f32_16x16x32_bf16 v[114:117], v[154:157], v[204:207], v[114:117]
	v_mfma_f32_16x16x32_bf16 v[118:121], v[180:183], v[204:207], v[118:121]
	v_mfma_f32_16x16x32_bf16 v[122:125], v[154:157], v[212:215], v[122:125]
	v_mfma_f32_16x16x32_bf16 v[126:129], v[180:183], v[212:215], v[126:129]
	s_setprio 0
	s_barrier
; #define PG8_STAGE(bufoff, gbase) do { _Pragma("unroll") for (int _i = 0; _i < 2; ++_i) \
;     __builtin_amdgcn_global_load_lds((const unsigned*)((const char*)(gbase) + voff[_i]), (LAS unsigned*)(lds + (bufoff) + ldsw + _i * 8192), 16, 0, 0); } while (0)
; #define PG8_LDA(dst, b, h) do { _Pragma("unroll") for (int m = 0; m < 4; ++m) _Pragma("unroll") for (int k = 0; k < 2; ++k) dst[m][k] = *(const LAS bf16x8*)(lds + PG8_SA(b, h) + aoff + m * 2048 + k * 1024); } while (0)
; #define PG8_LDB(dst, b, h) do { _Pragma("unroll") for (int n = 0; n < 2; ++n) _Pragma("unroll") for (int k = 0; k < 2; ++k) dst[n][k] = *(const LAS bf16x8*)(lds + PG8_SB(b, h) + boff + n * 2048 + k * 1024); } while (0)
; #define PG8_MMA(ai, bj, At, Bt_) do { __builtin_amdgcn_s_setprio(1); _Pragma("unroll") for (int m = 0; m < 4; ++m) _Pragma("unroll") for (int n = 0; n < 2; ++n) _Pragma("unroll") for (int k = 0; k < 2; ++k) \
;     acc[ai][bj][m][n] = __builtin_amdgcn_mfma_f32_16x16x32_bf16(Bt_[n][k], At[m][k], acc[ai][bj][m][n], 0, 0, 0); __builtin_amdgcn_s_setprio(0); } while (0)
; #define PG8_WAIT_V(n) asm volatile("s_waitcnt vmcnt(" #n ")" ::: "memory")
; #define PG8_WAIT_L(n) asm volatile("s_waitcnt lgkmcnt(" #n ")" ::: "memory")
; #define PG8_BAR __builtin_amdgcn_s_barrier()
; #define PG8_SCHED __builtin_amdgcn_sched_barrier(0)
; template <int EPI>
; __device__ __forceinline__ void gemm_phase(KP P, const bfu* __restrict__ A, const bfu* __restrict__ Bt, int K, int ntn, char* smem, const int wv) {
;     ...
;       PG8_STAGE(PG8_SB(0, 1), b2 + hstep);
;       PG8_WAIT_V(6); PG8_BAR; PG8_MMA(1, 1, At, B1); PG8_BAR;
;       PG8_LDB(B0, 1, 0); PG8_SCHED; PG8_LDA(At, 1, 0); PG8_STAGE(PG8_SA(0, 1), a2 + hstep);
;       PG8_WAIT_L(8); PG8_BAR; PG8_WAIT_L(0); PG8_MMA(0, 0, At, B0); PG8_BAR; PG8_SCHED;
;       PG8_LDB(B1, 1, 1); PG8_STAGE(PG8_SB(1, 0), b3);
;       PG8_BAR; PG8_WAIT_L(0); PG8_MMA(0, 1, At, B1); PG8_BAR;
;       PG8_LDA(At, 1, 1); PG8_STAGE(PG8_SA(1, 0), a3);
	s_add_u32 s22, s22, s60
	s_addc_u32 s23, s23, 0
	s_mov_b32 m0, s41
	v_lshl_add_u64 v[236:237], s[22:23], 0, v[130:131]
	global_load_lds_dwordx4 v[236:237], off
	v_lshl_add_u64 v[238:239], s[22:23], 0, v[132:133]
	s_mov_b32 m0, s42
	s_nop 0
	global_load_lds_dwordx4 v[238:239], off
	s_waitcnt vmcnt(6)
	s_barrier
	s_setprio 1
	v_mfma_f32_16x16x32_bf16 v[106:109], v[216:219], v[184:187], v[106:109]
	v_mfma_f32_16x16x32_bf16 v[110:113], v[224:227], v[184:187], v[110:113]
	v_mfma_f32_16x16x32_bf16 v[82:85], v[216:219], v[192:195], v[82:85]
	v_mfma_f32_16x16x32_bf16 v[74:77], v[224:227], v[192:195], v[74:77]
	v_mfma_f32_16x16x32_bf16 v[90:93], v[216:219], v[200:203], v[90:93]
	v_mfma_f32_16x16x32_bf16 v[78:81], v[224:227], v[200:203], v[78:81]
	v_mfma_f32_16x16x32_bf16 v[94:97], v[216:219], v[208:211], v[94:97]
	v_mfma_f32_16x16x32_bf16 v[86:89], v[224:227], v[208:211], v[86:89]
	v_mfma_f32_16x16x32_bf16 v[106:109], v[220:223], v[188:191], v[106:109]
	v_mfma_f32_16x16x32_bf16 v[110:113], v[228:231], v[188:191], v[110:113]
	v_mfma_f32_16x16x32_bf16 v[82:85], v[220:223], v[196:199], v[82:85]
	v_mfma_f32_16x16x32_bf16 v[74:77], v[228:231], v[196:199], v[74:77]
	v_mfma_f32_16x16x32_bf16 v[90:93], v[220:223], v[204:207], v[90:93]
	v_mfma_f32_16x16x32_bf16 v[78:81], v[228:231], v[204:207], v[78:81]
	v_mfma_f32_16x16x32_bf16 v[94:97], v[220:223], v[212:215], v[94:97]
	v_mfma_f32_16x16x32_bf16 v[86:89], v[228:231], v[212:215], v[86:89]
	s_setprio 0
	v_add_u32_e32 v0, s45, v142
	s_barrier
	ds_read_b128 v[150:153], v0
	ds_read_b128 v[154:157], v0 offset:1024
	ds_read_b128 v[158:161], v0 offset:2048
	ds_read_b128 v[180:183], v0 offset:3072
	s_add_u32 s18, s18, s60
	s_addc_u32 s19, s19, 0
	s_mov_b32 m0, s43
	v_lshl_add_u64 v[216:217], s[18:19], 0, v[130:131]
	ds_read_b128 v[184:187], v143 offset:32768
	ds_read_b128 v[188:191], v143 offset:33792
	ds_read_b128 v[192:195], v143 offset:34816
	ds_read_b128 v[196:199], v143 offset:35840
	ds_read_b128 v[200:203], v143 offset:36864
	ds_read_b128 v[204:207], v143 offset:37888
	ds_read_b128 v[208:211], v143 offset:38912
	ds_read_b128 v[212:215], v143 offset:39936
	global_load_lds_dwordx4 v[216:217], off
	v_lshl_add_u64 v[216:217], s[18:19], 0, v[132:133]
	s_mov_b32 m0, s44
	s_nop 0
	global_load_lds_dwordx4 v[216:217], off
	s_waitcnt lgkmcnt(8)
	s_barrier
	s_waitcnt lgkmcnt(0)
	s_setprio 1
	s_waitcnt lgkmcnt(0)
	v_mfma_f32_16x16x32_bf16 v[2:5], v[150:153], v[184:187], v[2:5]
	v_mfma_f32_16x16x32_bf16 v[6:9], v[158:161], v[184:187], v[6:9]
	v_mfma_f32_16x16x32_bf16 v[10:13], v[150:153], v[192:195], v[10:13]
	v_mfma_f32_16x16x32_bf16 v[14:17], v[158:161], v[192:195], v[14:17]
	v_mfma_f32_16x16x32_bf16 v[26:29], v[150:153], v[200:203], v[26:29]
	v_mfma_f32_16x16x32_bf16 v[30:33], v[158:161], v[200:203], v[30:33]
	v_mfma_f32_16x16x32_bf16 v[42:45], v[150:153], v[208:211], v[42:45]
	v_mfma_f32_16x16x32_bf16 v[46:49], v[158:161], v[208:211], v[46:49]
	v_mfma_f32_16x16x32_bf16 v[2:5], v[154:157], v[188:191], v[2:5]
	v_mfma_f32_16x16x32_bf16 v[6:9], v[180:183], v[188:191], v[6:9]
	v_mfma_f32_16x16x32_bf16 v[10:13], v[154:157], v[196:199], v[10:13]
	v_mfma_f32_16x16x32_bf16 v[14:17], v[180:183], v[196:199], v[14:17]
	v_mfma_f32_16x16x32_bf16 v[26:29], v[154:157], v[204:207], v[26:29]
	v_mfma_f32_16x16x32_bf16 v[30:33], v[180:183], v[204:207], v[30:33]
	v_mfma_f32_16x16x32_bf16 v[42:45], v[154:157], v[212:215], v[42:45]
	v_mfma_f32_16x16x32_bf16 v[46:49], v[180:183], v[212:215], v[46:49]
	s_setprio 0
	s_barrier
	s_mov_b32 m0, s46
	v_add_u32_e32 v0, s50, v142
	v_lshl_add_u64 v[144:145], v[144:145], 0, s[90:91]
	ds_read_b128 v[216:219], v0
	ds_read_b128 v[220:223], v0 offset:1024
	ds_read_b128 v[224:227], v0 offset:2048
	ds_read_b128 v[228:231], v0 offset:3072
	global_load_lds_dwordx4 v[144:145], off
	v_lshl_add_u64 v[144:145], v[162:163], 0, s[90:91]
	s_mov_b32 m0, s47
	s_nop 0
	global_load_lds_dwordx4 v[144:145], off
	s_barrier
	s_waitcnt lgkmcnt(0)
	s_setprio 1
	s_waitcnt lgkmcnt(0)
	v_mfma_f32_16x16x32_bf16 v[18:21], v[216:219], v[184:187], v[18:21]
	v_mfma_f32_16x16x32_bf16 v[22:25], v[224:227], v[184:187], v[22:25]
	v_mfma_f32_16x16x32_bf16 v[34:37], v[216:219], v[192:195], v[34:37]
	v_mfma_f32_16x16x32_bf16 v[38:41], v[224:227], v[192:195], v[38:41]
	v_mfma_f32_16x16x32_bf16 v[50:53], v[216:219], v[200:203], v[50:53]
	v_mfma_f32_16x16x32_bf16 v[54:57], v[224:227], v[200:203], v[54:57]
	v_mfma_f32_16x16x32_bf16 v[58:61], v[216:219], v[208:211], v[58:61]
	v_mfma_f32_16x16x32_bf16 v[62:65], v[224:227], v[208:211], v[62:65]
	v_mfma_f32_16x16x32_bf16 v[18:21], v[220:223], v[188:191], v[18:21]
	v_mfma_f32_16x16x32_bf16 v[22:25], v[228:231], v[188:191], v[22:25]
	v_mfma_f32_16x16x32_bf16 v[34:37], v[220:223], v[196:199], v[34:37]
	v_mfma_f32_16x16x32_bf16 v[38:41], v[228:231], v[196:199], v[38:41]
	v_mfma_f32_16x16x32_bf16 v[50:53], v[220:223], v[204:207], v[50:53]
	v_mfma_f32_16x16x32_bf16 v[54:57], v[228:231], v[204:207], v[54:57]
	v_mfma_f32_16x16x32_bf16 v[58:61], v[220:223], v[212:215], v[58:61]
	v_mfma_f32_16x16x32_bf16 v[62:65], v[228:231], v[212:215], v[62:65]
	s_setprio 0
	s_mov_b32 m0, s48
	v_lshl_add_u64 v[144:145], v[232:233], 0, s[90:91]
	s_barrier
	ds_read_b128 v[184:187], v143 offset:49152
	ds_read_b128 v[188:191], v143 offset:50176
	ds_read_b128 v[192:195], v143 offset:51200
	ds_read_b128 v[196:199], v143 offset:52224
	ds_read_b128 v[200:203], v143 offset:53248
	ds_read_b128 v[204:207], v143 offset:54272
	ds_read_b128 v[208:211], v143 offset:55296
	ds_read_b128 v[212:215], v143 offset:56320
	global_load_lds_dwordx4 v[144:145], off
	v_lshl_add_u64 v[144:145], v[234:235], 0, s[90:91]
	s_mov_b32 m0, s49
	s_nop 0
	global_load_lds_dwordx4 v[144:145], off
	s_barrier
; #define PG8_STAGE(bufoff, gbase) do { _Pragma("unroll") for (int _i = 0; _i < 2; ++_i) \
;     __builtin_amdgcn_global_load_lds((const unsigned*)((const char*)(gbase) + voff[_i]), (LAS unsigned*)(lds + (bufoff) + ldsw + _i * 8192), 16, 0, 0); } while (0)
; #define PG8_MMA(ai, bj, At, Bt_) do { __builtin_amdgcn_s_setprio(1); _Pragma("unroll") for (int m = 0; m < 4; ++m) _Pragma("unroll") for (int n = 0; n < 2; ++n) _Pragma("unroll") for (int k = 0; k < 2; ++k) \
;     acc[ai][bj][m][n] = __builtin_amdgcn_mfma_f32_16x16x32_bf16(Bt_[n][k], At[m][k], acc[ai][bj][m][n], 0, 0, 0); __builtin_amdgcn_s_setprio(0); } while (0)
; #define PG8_WAIT_V(n) asm volatile("s_waitcnt vmcnt(" #n ")" ::: "memory")
; #define PG8_WAIT_L(n) asm volatile("s_waitcnt lgkmcnt(" #n ")" ::: "memory")
; #define PG8_BAR __builtin_amdgcn_s_barrier()
; #define PG8_SCHED __builtin_amdgcn_sched_barrier(0)
; template <int EPI>
; __device__ __forceinline__ void gemm_epilogue(KP P, f32x4 (&acc)[2][2][4][2], int brow, int bcol, int wr, int wc, int fr_, int fq_, const float* sRu) {
;     ...
;   } else if (EPI == EPI_OUTPROJ || EPI == EPI_RES) {
;     bfu* xo = (bfu*)(P->ws + WS_XR) + (size_t)brow * D + bcol;
; #pragma unroll
;     for (int ai = 0; ai < 2; ++ai)
; #pragma unroll
;       for (int m = 0; m < 4; ++m) {
;         __builtin_amdgcn_sched_barrier(0);
;         unsigned lr = lrow0 + ai * 128 + m * 16;
;         unsigned o = lr * D + lcol0;
;         float rsd = 1.f;
;         if (EPI == EPI_OUTPROJ) rsd = sRu[lr];
; #pragma unroll
;         for (int bj = 0; bj < 2; ++bj)
; #pragma unroll
;           for (int n = 0; n < 2; ++n) {
;             f32x4 v = acc[ai][bj][m][n] * rsd;
;             uint2 pk; pk.x = cvt_pk_bf16(v[0], v[1]); pk.y = cvt_pk_bf16(v[2], v[3]);
;             *(uint2*)(xo + o + bj * 128 + n * 16) = pk;
;           }
;       }
; template <int EPI>
; __device__ __forceinline__ void gemm_phase(KP P, const bfu* __restrict__ A, const bfu* __restrict__ Bt, int K, int ntn, char* smem, const int wv) {
;     ...
;       PG8_BAR; PG8_WAIT_L(0); PG8_MMA(1, 0, At, B0); PG8_BAR; PG8_SCHED;
;       PG8_STAGE(PG8_SB(1, 1), b3 + hstep);
;       PG8_WAIT_V(6); PG8_BAR; PG8_MMA(1, 1, At, B1); PG8_BAR;
;     }
	s_waitcnt lgkmcnt(0)
	s_setprio 1
	s_waitcnt lgkmcnt(0)
	v_mfma_f32_16x16x32_bf16 v[66:69], v[150:153], v[184:187], v[66:69]
	v_mfma_f32_16x16x32_bf16 v[70:73], v[158:161], v[184:187], v[70:73]
	v_mfma_f32_16x16x32_bf16 v[98:101], v[150:153], v[192:195], v[98:101]
	v_mfma_f32_16x16x32_bf16 v[102:105], v[158:161], v[192:195], v[102:105]
	v_mfma_f32_16x16x32_bf16 v[114:117], v[150:153], v[200:203], v[114:117]
	v_mfma_f32_16x16x32_bf16 v[118:121], v[158:161], v[200:203], v[118:121]
	v_mfma_f32_16x16x32_bf16 v[122:125], v[150:153], v[208:211], v[122:125]
	v_mfma_f32_16x16x32_bf16 v[126:129], v[158:161], v[208:211], v[126:129]
	v_mfma_f32_16x16x32_bf16 v[66:69], v[154:157], v[188:191], v[66:69]
	v_mfma_f32_16x16x32_bf16 v[70:73], v[180:183], v[188:191], v[70:73]
	v_mfma_f32_16x16x32_bf16 v[98:101], v[154:157], v[196:199], v[98:101]
	v_mfma_f32_16x16x32_bf16 v[102:105], v[180:183], v[196:199], v[102:105]
	v_mfma_f32_16x16x32_bf16 v[114:117], v[154:157], v[204:207], v[114:117]
	v_mfma_f32_16x16x32_bf16 v[118:121], v[180:183], v[204:207], v[118:121]
	v_mfma_f32_16x16x32_bf16 v[122:125], v[154:157], v[212:215], v[122:125]
	v_mfma_f32_16x16x32_bf16 v[126:129], v[180:183], v[212:215], v[126:129]
	s_setprio 0
	s_barrier
	s_mov_b32 m0, s51
	v_lshl_add_u64 v[144:145], v[236:237], 0, s[90:91]
	global_load_lds_dwordx4 v[144:145], off
	v_lshl_add_u64 v[144:145], v[238:239], 0, s[90:91]
	s_mov_b32 m0, s52
	s_nop 0
	global_load_lds_dwordx4 v[144:145], off
	s_waitcnt vmcnt(6)
	s_barrier
	s_setprio 1
	v_mfma_f32_16x16x32_bf16 v[106:109], v[216:219], v[184:187], v[106:109]
	v_mfma_f32_16x16x32_bf16 v[110:113], v[224:227], v[184:187], v[110:113]
	v_mfma_f32_16x16x32_bf16 v[82:85], v[216:219], v[192:195], v[82:85]
	v_mfma_f32_16x16x32_bf16 v[74:77], v[224:227], v[192:195], v[74:77]
	v_mfma_f32_16x16x32_bf16 v[90:93], v[216:219], v[200:203], v[90:93]
	v_mfma_f32_16x16x32_bf16 v[78:81], v[224:227], v[200:203], v[78:81]
	v_mfma_f32_16x16x32_bf16 v[94:97], v[216:219], v[208:211], v[94:97]
	v_mfma_f32_16x16x32_bf16 v[86:89], v[224:227], v[208:211], v[86:89]
	v_mfma_f32_16x16x32_bf16 v[106:109], v[220:223], v[188:191], v[106:109]
	v_mfma_f32_16x16x32_bf16 v[110:113], v[228:231], v[188:191], v[110:113]
	v_mfma_f32_16x16x32_bf16 v[82:85], v[220:223], v[196:199], v[82:85]
	v_mfma_f32_16x16x32_bf16 v[74:77], v[228:231], v[196:199], v[74:77]
	v_mfma_f32_16x16x32_bf16 v[90:93], v[220:223], v[204:207], v[90:93]
	v_mfma_f32_16x16x32_bf16 v[78:81], v[228:231], v[204:207], v[78:81]
	v_mfma_f32_16x16x32_bf16 v[94:97], v[220:223], v[212:215], v[94:97]
	v_mfma_f32_16x16x32_bf16 v[86:89], v[228:231], v[212:215], v[86:89]
	s_setprio 0
	s_add_u32 s20, s20, 0x100
	s_addc_u32 s21, s21, 0
	s_add_u32 s80, s80, 0x100
	s_addc_u32 s81, s81, 0
	s_cmp_ge_u32 s82, s62
	s_mov_b32 s18, s82
	s_barrier
	s_cbranch_scc0 .LBB0_283
	s_lshl_b32 s18, s77, 8
	s_ashr_i32 s19, s18, 31
	s_lshl_b32 s20, s76, 8
	s_lshl_b64 s[18:19], s[18:19], 11
	s_add_u32 s22, s4, s18
	s_addc_u32 s23, s5, s19
	s_ashr_i32 s21, s20, 31
	v_mov_b32_e32 v0, v140
	v_mov_b32_e32 v144, v135
	s_lshl_b64 s[18:19], s[20:21], 1
	s_add_u32 s18, s22, s18
	v_lshlrev_b32_e32 v144, 2, v144
	v_and_b32_e32 v208, 1, v135
	v_mul_u32_u24_e32 v208, 12, v208
	v_add_u32_e32 v144, v144, v208
	s_addc_u32 s19, s23, s19
	v_lshlrev_b32_e32 v0, 10, v0
	v_add3_u32 v0, s66, v144, v0
	v_lshl_add_u64 v[144:145], v[0:1], 1, s[18:19]
	v_cvt_pk_bf16_f32 v200, v2, v3
	v_cvt_pk_bf16_f32 v201, v4, v5
	v_cvt_pk_bf16_f32 v202, v6, v7
	v_cvt_pk_bf16_f32 v203, v8, v9
	s_nop 1
	v_permlane16_swap_b32_e32 v200, v202
	v_permlane16_swap_b32_e32 v201, v203
	global_store_dwordx4 v[144:145], v[200:203], off
	v_cvt_pk_bf16_f32 v204, v18, v19
	v_cvt_pk_bf16_f32 v205, v20, v21
	v_cvt_pk_bf16_f32 v206, v22, v23
	v_cvt_pk_bf16_f32 v207, v24, v25
	s_nop 1
	v_permlane16_swap_b32_e32 v204, v206
	v_permlane16_swap_b32_e32 v205, v207
	global_store_dwordx4 v[144:145], v[204:207], off offset:256
	v_add_u32_e32 v2, 0x4000, v0
	v_mov_b32_e32 v3, v1
	v_lshl_add_u64 v[2:3], v[2:3], 1, s[18:19]
	v_cvt_pk_bf16_f32 v200, v10, v11
	v_cvt_pk_bf16_f32 v201, v12, v13
	v_cvt_pk_bf16_f32 v202, v14, v15
	v_cvt_pk_bf16_f32 v203, v16, v17
	s_nop 1
	v_permlane16_swap_b32_e32 v200, v202
	v_permlane16_swap_b32_e32 v201, v203
	global_store_dwordx4 v[2:3], v[200:203], off
	v_cvt_pk_bf16_f32 v204, v34, v35
	v_cvt_pk_bf16_f32 v205, v36, v37
	v_cvt_pk_bf16_f32 v206, v38, v39
	v_cvt_pk_bf16_f32 v207, v40, v41
	s_nop 1
	v_permlane16_swap_b32_e32 v204, v206
	v_permlane16_swap_b32_e32 v205, v207
	global_store_dwordx4 v[2:3], v[204:207], off offset:256
	v_add_u32_e32 v2, 0x8000, v0
	v_mov_b32_e32 v3, v1
	v_lshl_add_u64 v[2:3], v[2:3], 1, s[18:19]
	v_cvt_pk_bf16_f32 v200, v26, v27
	v_cvt_pk_bf16_f32 v201, v28, v29
	v_cvt_pk_bf16_f32 v202, v30, v31
	v_cvt_pk_bf16_f32 v203, v32, v33
	s_nop 1
	v_permlane16_swap_b32_e32 v200, v202
	v_permlane16_swap_b32_e32 v201, v203
	global_store_dwordx4 v[2:3], v[200:203], off
	v_cvt_pk_bf16_f32 v204, v50, v51
	v_cvt_pk_bf16_f32 v205, v52, v53
	v_cvt_pk_bf16_f32 v206, v54, v55
	v_cvt_pk_bf16_f32 v207, v56, v57
	s_nop 1
	v_permlane16_swap_b32_e32 v204, v206
	v_permlane16_swap_b32_e32 v205, v207
	global_store_dwordx4 v[2:3], v[204:207], off offset:256
	v_add_u32_e32 v2, 0xc000, v0
	v_mov_b32_e32 v3, v1
	v_lshl_add_u64 v[2:3], v[2:3], 1, s[18:19]
	v_cvt_pk_bf16_f32 v200, v42, v43
	v_cvt_pk_bf16_f32 v201, v44, v45
	v_cvt_pk_bf16_f32 v202, v46, v47
	v_cvt_pk_bf16_f32 v203, v48, v49
	s_nop 1
	v_permlane16_swap_b32_e32 v200, v202
	v_permlane16_swap_b32_e32 v201, v203
	global_store_dwordx4 v[2:3], v[200:203], off
	v_cvt_pk_bf16_f32 v204, v58, v59
	v_cvt_pk_bf16_f32 v205, v60, v61
; template <int EPI>
; __device__ __forceinline__ void gemm_acc_init(KP P, f32x4 (&acc)[2][2][4][2], int brow, int bcol, int wr, int wc, int fr_, int fq_, const float* sRu) {
;     ...
;     const float* xin = (brow < MP ? P->in[0] + (size_t)brow * D : P->in[1] + (size_t)(brow - MP) * D) + bcol;
;     const bfu* xrb = (const bfu*)(P->ws + WS_XR) + (size_t)brow * D + bcol;
; #pragma unroll
;     for (int ai = 0; ai < 2; ++ai)
; #pragma unroll
;       for (int m = 0; m < 4; ++m) {
;         __builtin_amdgcn_sched_barrier(0);
;         unsigned lr = ai * 128 + wr * 64 + m * 16 + fr;
;         unsigned o = lr * D + wc * 32 + fq * 4;
;         float sc = 1.f;
;         if (EPI == EPI_OUTPROJ) sc = 1.f / sRu[lr];
; #pragma unroll
;         for (int bj = 0; bj < 2; ++bj)
; #pragma unroll
;           for (int n = 0; n < 2; ++n) {
;             if (EPI == EPI_RES) acc[ai][bj][m][n] = bf4_to_f32(*(const uint2*)(xrb + o + bj * 128 + n * 16));
;             else acc[ai][bj][m][n] = *(const f32x4*)(xin + o + bj * 128 + n * 16) * sc;
;           }
;       }
; template <int EPI>
; __device__ __forceinline__ void gemm_epilogue(KP P, f32x4 (&acc)[2][2][4][2], int brow, int bcol, int wr, int wc, int fr_, int fq_, const float* sRu) {
;     ...
;   } else if (EPI == EPI_OUTPROJ || EPI == EPI_RES) {
;     bfu* xo = (bfu*)(P->ws + WS_XR) + (size_t)brow * D + bcol;
; #pragma unroll
;     for (int ai = 0; ai < 2; ++ai)
; #pragma unroll
;       for (int m = 0; m < 4; ++m) {
;         __builtin_amdgcn_sched_barrier(0);
;         unsigned lr = lrow0 + ai * 128 + m * 16;
;         unsigned o = lr * D + lcol0;
;         float rsd = 1.f;
;         if (EPI == EPI_OUTPROJ) rsd = sRu[lr];
; #pragma unroll
;         for (int bj = 0; bj < 2; ++bj)
; #pragma unroll
;           for (int n = 0; n < 2; ++n) {
;             f32x4 v = acc[ai][bj][m][n] * rsd;
;             uint2 pk; pk.x = cvt_pk_bf16(v[0], v[1]); pk.y = cvt_pk_bf16(v[2], v[3]);
;             *(uint2*)(xo + o + bj * 128 + n * 16) = pk;
;           }
;       }
	v_cvt_pk_bf16_f32 v206, v62, v63
	v_cvt_pk_bf16_f32 v207, v64, v65
	s_nop 1
	v_permlane16_swap_b32_e32 v204, v206
	v_permlane16_swap_b32_e32 v205, v207
	global_store_dwordx4 v[2:3], v[204:207], off offset:256
	v_add_u32_e32 v2, 0x20000, v0
	v_mov_b32_e32 v3, v1
	v_lshl_add_u64 v[2:3], v[2:3], 1, s[18:19]
	v_cvt_pk_bf16_f32 v200, v66, v67
	v_cvt_pk_bf16_f32 v201, v68, v69
	v_cvt_pk_bf16_f32 v202, v70, v71
	v_cvt_pk_bf16_f32 v203, v72, v73
	s_nop 1
	v_permlane16_swap_b32_e32 v200, v202
	v_permlane16_swap_b32_e32 v201, v203
	global_store_dwordx4 v[2:3], v[200:203], off
	v_cvt_pk_bf16_f32 v204, v106, v107
	v_cvt_pk_bf16_f32 v205, v108, v109
	v_cvt_pk_bf16_f32 v206, v110, v111
	v_cvt_pk_bf16_f32 v207, v112, v113
	s_nop 1
	v_permlane16_swap_b32_e32 v204, v206
	v_permlane16_swap_b32_e32 v205, v207
	global_store_dwordx4 v[2:3], v[204:207], off offset:256
	v_add_u32_e32 v2, 0x24000, v0
	v_mov_b32_e32 v3, v1
	v_lshl_add_u64 v[2:3], v[2:3], 1, s[18:19]
	v_cvt_pk_bf16_f32 v200, v98, v99
	v_cvt_pk_bf16_f32 v201, v100, v101
	v_cvt_pk_bf16_f32 v202, v102, v103
	v_cvt_pk_bf16_f32 v203, v104, v105
	s_nop 1
	v_permlane16_swap_b32_e32 v200, v202
	v_permlane16_swap_b32_e32 v201, v203
	global_store_dwordx4 v[2:3], v[200:203], off
	v_cvt_pk_bf16_f32 v204, v82, v83
	v_cvt_pk_bf16_f32 v205, v84, v85
	v_cvt_pk_bf16_f32 v206, v74, v75
	v_cvt_pk_bf16_f32 v207, v76, v77
	s_nop 1
	v_permlane16_swap_b32_e32 v204, v206
	v_permlane16_swap_b32_e32 v205, v207
	global_store_dwordx4 v[2:3], v[204:207], off offset:256
	v_add_u32_e32 v2, 0x28000, v0
	v_mov_b32_e32 v3, v1
	v_lshl_add_u64 v[2:3], v[2:3], 1, s[18:19]
	v_cvt_pk_bf16_f32 v200, v114, v115
	v_cvt_pk_bf16_f32 v201, v116, v117
	v_cvt_pk_bf16_f32 v202, v118, v119
	v_cvt_pk_bf16_f32 v203, v120, v121
	s_nop 1
	v_permlane16_swap_b32_e32 v200, v202
	v_permlane16_swap_b32_e32 v201, v203
	global_store_dwordx4 v[2:3], v[200:203], off
	v_cvt_pk_bf16_f32 v204, v90, v91
	v_cvt_pk_bf16_f32 v205, v92, v93
	v_cvt_pk_bf16_f32 v206, v78, v79
	v_cvt_pk_bf16_f32 v207, v80, v81
	s_nop 1
	v_permlane16_swap_b32_e32 v204, v206
	v_permlane16_swap_b32_e32 v205, v207
	global_store_dwordx4 v[2:3], v[204:207], off offset:256
	v_add_u32_e32 v0, 0x2c000, v0
	v_lshl_add_u64 v[2:3], v[0:1], 1, s[18:19]
	v_cvt_pk_bf16_f32 v200, v122, v123
	v_cvt_pk_bf16_f32 v201, v124, v125
	v_cvt_pk_bf16_f32 v202, v126, v127
	v_cvt_pk_bf16_f32 v203, v128, v129
	s_nop 1
	v_permlane16_swap_b32_e32 v200, v202
	v_permlane16_swap_b32_e32 v201, v203
	global_store_dwordx4 v[2:3], v[200:203], off
	v_cvt_pk_bf16_f32 v204, v94, v95
	v_cvt_pk_bf16_f32 v205, v96, v97
	v_cvt_pk_bf16_f32 v206, v86, v87
	v_cvt_pk_bf16_f32 v207, v88, v89
	s_mov_b64 s[18:19], -1
	s_and_b64 vcc, exec, s[16:17]
	s_nop 1
	v_permlane16_swap_b32_e32 v204, v206
	v_permlane16_swap_b32_e32 v205, v207
	global_store_dwordx4 v[2:3], v[204:207], off offset:256
	s_cbranch_vccz .LBB0_279
	s_lshl_b32 s16, s75, 8
	s_lshl_b32 s18, s74, 8
	s_ashr_i32 s17, s16, 31
	s_ashr_i32 s19, s18, 31
	s_lshl_b64 s[16:17], s[16:17], 11
	s_add_u32 s20, s4, s16
	v_mov_b32_e32 v0, v135
	v_mov_b32_e32 v2, v140
	s_addc_u32 s21, s5, s17
	s_lshl_b64 s[16:17], s[18:19], 1
	s_add_u32 s16, s20, s16
	s_addc_u32 s17, s21, s17
	v_lshlrev_b32_e32 v0, 2, v0
	v_lshlrev_b32_e32 v2, 10, v2
	v_add3_u32 v0, s66, v0, v2
	v_lshl_add_u64 v[200:201], v[0:1], 1, s[16:17]
	global_load_dwordx2 v[4:5], v[200:201], off
	global_load_dwordx2 v[8:9], v[200:201], off offset:32
	global_load_dwordx2 v[20:21], v[200:201], off offset:256
	global_load_dwordx2 v[24:25], v[200:201], off offset:288
	v_add_u32_e32 v202, 0x4000, v0
	v_mov_b32_e32 v203, v1
	v_lshl_add_u64 v[202:203], v[202:203], 1, s[16:17]
	global_load_dwordx2 v[12:13], v[202:203], off
	global_load_dwordx2 v[16:17], v[202:203], off offset:32
	global_load_dwordx2 v[36:37], v[202:203], off offset:256
	global_load_dwordx2 v[40:41], v[202:203], off offset:288
	v_add_u32_e32 v204, 0x8000, v0
	v_mov_b32_e32 v205, v1
	v_lshl_add_u64 v[204:205], v[204:205], 1, s[16:17]
	global_load_dwordx2 v[28:29], v[204:205], off
	global_load_dwordx2 v[32:33], v[204:205], off offset:32
	global_load_dwordx2 v[52:53], v[204:205], off offset:256
	global_load_dwordx2 v[56:57], v[204:205], off offset:288
	v_add_u32_e32 v206, 0xc000, v0
	v_mov_b32_e32 v207, v1
	v_lshl_add_u64 v[206:207], v[206:207], 1, s[16:17]
	global_load_dwordx2 v[44:45], v[206:207], off
	global_load_dwordx2 v[48:49], v[206:207], off offset:32
	global_load_dwordx2 v[60:61], v[206:207], off offset:256
	global_load_dwordx2 v[64:65], v[206:207], off offset:288
	v_add_u32_e32 v208, 0x20000, v0
	v_mov_b32_e32 v209, v1
	v_lshl_add_u64 v[208:209], v[208:209], 1, s[16:17]
	global_load_dwordx2 v[68:69], v[208:209], off
	global_load_dwordx2 v[72:73], v[208:209], off offset:32
	global_load_dwordx2 v[108:109], v[208:209], off offset:256
	global_load_dwordx2 v[112:113], v[208:209], off offset:288
	v_add_u32_e32 v210, 0x24000, v0
	v_mov_b32_e32 v211, v1
	v_lshl_add_u64 v[210:211], v[210:211], 1, s[16:17]
	global_load_dwordx2 v[100:101], v[210:211], off
	global_load_dwordx2 v[104:105], v[210:211], off offset:32
	global_load_dwordx2 v[84:85], v[210:211], off offset:256
	global_load_dwordx2 v[76:77], v[210:211], off offset:288
	v_add_u32_e32 v212, 0x28000, v0
	v_mov_b32_e32 v213, v1
	v_lshl_add_u64 v[212:213], v[212:213], 1, s[16:17]
	global_load_dwordx2 v[116:117], v[212:213], off
	global_load_dwordx2 v[120:121], v[212:213], off offset:32
	global_load_dwordx2 v[92:93], v[212:213], off offset:256
	global_load_dwordx2 v[80:81], v[212:213], off offset:288
	v_add_u32_e32 v214, 0x2c000, v0
	v_mov_b32_e32 v215, v1
	v_lshl_add_u64 v[214:215], v[214:215], 1, s[16:17]
	global_load_dwordx2 v[124:125], v[214:215], off
	global_load_dwordx2 v[128:129], v[214:215], off offset:32
	global_load_dwordx2 v[96:97], v[214:215], off offset:256
	global_load_dwordx2 v[88:89], v[214:215], off offset:288
	s_waitcnt vmcnt(0)
; template <int EPI>
; __device__ __forceinline__ void gemm_acc_init(KP P, f32x4 (&acc)[2][2][4][2], int brow, int bcol, int wr, int wc, int fr_, int fq_, const float* sRu) {
;     ...
;     const float* xin = (brow < MP ? P->in[0] + (size_t)brow * D : P->in[1] + (size_t)(brow - MP) * D) + bcol;
;     const bfu* xrb = (const bfu*)(P->ws + WS_XR) + (size_t)brow * D + bcol;
; #pragma unroll
;     for (int ai = 0; ai < 2; ++ai)
; #pragma unroll
;       for (int m = 0; m < 4; ++m) {
;         __builtin_amdgcn_sched_barrier(0);
;         unsigned lr = ai * 128 + wr * 64 + m * 16 + fr;
;         unsigned o = lr * D + wc * 32 + fq * 4;
;         float sc = 1.f;
;         if (EPI == EPI_OUTPROJ) sc = 1.f / sRu[lr];
; #pragma unroll
;         for (int bj = 0; bj < 2; ++bj)
; #pragma unroll
;           for (int n = 0; n < 2; ++n) {
;             if (EPI == EPI_RES) acc[ai][bj][m][n] = bf4_to_f32(*(const uint2*)(xrb + o + bj * 128 + n * 16));
;             else acc[ai][bj][m][n] = *(const f32x4*)(xin + o + bj * 128 + n * 16) * sc;
;           }
;       }
	v_lshlrev_b32_e32 v2, 16, v4
	v_and_b32_e32 v3, 0xffff0000, v4
	v_lshlrev_b32_e32 v4, 16, v5
	v_and_b32_e32 v5, 0xffff0000, v5
	v_lshlrev_b32_e32 v6, 16, v8
	v_and_b32_e32 v7, 0xffff0000, v8
	v_lshlrev_b32_e32 v8, 16, v9
	v_and_b32_e32 v9, 0xffff0000, v9
	v_lshlrev_b32_e32 v18, 16, v20
	v_and_b32_e32 v19, 0xffff0000, v20
	v_lshlrev_b32_e32 v20, 16, v21
	v_and_b32_e32 v21, 0xffff0000, v21
	v_lshlrev_b32_e32 v22, 16, v24
	v_and_b32_e32 v23, 0xffff0000, v24
	v_lshlrev_b32_e32 v24, 16, v25
	v_and_b32_e32 v25, 0xffff0000, v25
	v_lshlrev_b32_e32 v10, 16, v12
	v_and_b32_e32 v11, 0xffff0000, v12
	v_lshlrev_b32_e32 v12, 16, v13
	v_and_b32_e32 v13, 0xffff0000, v13
	v_lshlrev_b32_e32 v14, 16, v16
	v_and_b32_e32 v15, 0xffff0000, v16
	v_lshlrev_b32_e32 v16, 16, v17
	v_and_b32_e32 v17, 0xffff0000, v17
	v_lshlrev_b32_e32 v34, 16, v36
	v_and_b32_e32 v35, 0xffff0000, v36
	v_lshlrev_b32_e32 v36, 16, v37
	v_and_b32_e32 v37, 0xffff0000, v37
	v_lshlrev_b32_e32 v38, 16, v40
	v_and_b32_e32 v39, 0xffff0000, v40
	v_lshlrev_b32_e32 v40, 16, v41
	v_and_b32_e32 v41, 0xffff0000, v41
	v_lshlrev_b32_e32 v26, 16, v28
	v_and_b32_e32 v27, 0xffff0000, v28
	v_lshlrev_b32_e32 v28, 16, v29
	v_and_b32_e32 v29, 0xffff0000, v29
	v_lshlrev_b32_e32 v30, 16, v32
	v_and_b32_e32 v31, 0xffff0000, v32
	v_lshlrev_b32_e32 v32, 16, v33
	v_and_b32_e32 v33, 0xffff0000, v33
	v_lshlrev_b32_e32 v50, 16, v52
	v_and_b32_e32 v51, 0xffff0000, v52
	v_lshlrev_b32_e32 v52, 16, v53
	v_and_b32_e32 v53, 0xffff0000, v53
	v_lshlrev_b32_e32 v54, 16, v56
	v_and_b32_e32 v55, 0xffff0000, v56
	v_lshlrev_b32_e32 v56, 16, v57
	v_and_b32_e32 v57, 0xffff0000, v57
	v_lshlrev_b32_e32 v42, 16, v44
	v_and_b32_e32 v43, 0xffff0000, v44
	v_lshlrev_b32_e32 v44, 16, v45
	v_and_b32_e32 v45, 0xffff0000, v45
	v_lshlrev_b32_e32 v46, 16, v48
	v_and_b32_e32 v47, 0xffff0000, v48
	v_lshlrev_b32_e32 v48, 16, v49
	v_and_b32_e32 v49, 0xffff0000, v49
	v_lshlrev_b32_e32 v58, 16, v60
	v_and_b32_e32 v59, 0xffff0000, v60
	v_lshlrev_b32_e32 v60, 16, v61
	v_and_b32_e32 v61, 0xffff0000, v61
	v_lshlrev_b32_e32 v62, 16, v64
	v_and_b32_e32 v63, 0xffff0000, v64
	v_lshlrev_b32_e32 v64, 16, v65
	v_and_b32_e32 v65, 0xffff0000, v65
	v_lshlrev_b32_e32 v66, 16, v68
	v_and_b32_e32 v67, 0xffff0000, v68
	v_lshlrev_b32_e32 v68, 16, v69
	v_and_b32_e32 v69, 0xffff0000, v69
	v_lshlrev_b32_e32 v70, 16, v72
	v_and_b32_e32 v71, 0xffff0000, v72
	v_lshlrev_b32_e32 v72, 16, v73
	v_and_b32_e32 v73, 0xffff0000, v73
	v_lshlrev_b32_e32 v106, 16, v108
	v_and_b32_e32 v107, 0xffff0000, v108
	v_lshlrev_b32_e32 v108, 16, v109
	v_and_b32_e32 v109, 0xffff0000, v109
	v_lshlrev_b32_e32 v110, 16, v112
	v_and_b32_e32 v111, 0xffff0000, v112
	v_lshlrev_b32_e32 v112, 16, v113
	v_and_b32_e32 v113, 0xffff0000, v113
	v_lshlrev_b32_e32 v98, 16, v100
	v_and_b32_e32 v99, 0xffff0000, v100
	v_lshlrev_b32_e32 v100, 16, v101
	v_and_b32_e32 v101, 0xffff0000, v101
	v_lshlrev_b32_e32 v102, 16, v104
	v_and_b32_e32 v103, 0xffff0000, v104
	v_lshlrev_b32_e32 v104, 16, v105
	v_and_b32_e32 v105, 0xffff0000, v105
	v_lshlrev_b32_e32 v82, 16, v84
	v_and_b32_e32 v83, 0xffff0000, v84
	v_lshlrev_b32_e32 v84, 16, v85
	v_and_b32_e32 v85, 0xffff0000, v85
	v_lshlrev_b32_e32 v74, 16, v76
	v_and_b32_e32 v75, 0xffff0000, v76
	v_lshlrev_b32_e32 v76, 16, v77
	v_and_b32_e32 v77, 0xffff0000, v77
	v_lshlrev_b32_e32 v114, 16, v116
	v_and_b32_e32 v115, 0xffff0000, v116
	v_lshlrev_b32_e32 v116, 16, v117
	v_and_b32_e32 v117, 0xffff0000, v117
	v_lshlrev_b32_e32 v118, 16, v120
	v_and_b32_e32 v119, 0xffff0000, v120
	v_lshlrev_b32_e32 v120, 16, v121
	v_and_b32_e32 v121, 0xffff0000, v121
	v_lshlrev_b32_e32 v90, 16, v92
	v_and_b32_e32 v91, 0xffff0000, v92
	v_lshlrev_b32_e32 v92, 16, v93
	v_and_b32_e32 v93, 0xffff0000, v93
	v_lshlrev_b32_e32 v78, 16, v80
	v_and_b32_e32 v79, 0xffff0000, v80
	v_lshlrev_b32_e32 v80, 16, v81
	v_and_b32_e32 v81, 0xffff0000, v81
	v_lshlrev_b32_e32 v122, 16, v124
	v_and_b32_e32 v123, 0xffff0000, v124
	v_lshlrev_b32_e32 v124, 16, v125
	v_and_b32_e32 v125, 0xffff0000, v125
	v_lshlrev_b32_e32 v126, 16, v128
	v_and_b32_e32 v127, 0xffff0000, v128
	v_lshlrev_b32_e32 v128, 16, v129
	v_and_b32_e32 v129, 0xffff0000, v129
	v_lshlrev_b32_e32 v94, 16, v96
	v_and_b32_e32 v95, 0xffff0000, v96
	v_lshlrev_b32_e32 v96, 16, v97
	v_and_b32_e32 v97, 0xffff0000, v97
	v_lshlrev_b32_e32 v86, 16, v88
	v_and_b32_e32 v87, 0xffff0000, v88
	v_lshlrev_b32_e32 v88, 16, v89
	v_and_b32_e32 v89, 0xffff0000, v89
	s_mov_b64 s[18:19], 0
	s_branch .LBB0_279

; #define PG8_STAGE(bufoff, gbase) do { _Pragma("unroll") for (int _i = 0; _i < 2; ++_i) \
;     __builtin_amdgcn_global_load_lds((const unsigned*)((const char*)(gbase) + voff[_i]), (LAS unsigned*)(lds + (bufoff) + ldsw + _i * 8192), 16, 0, 0); } while (0)
; #define PG8_LDA(dst, b, h) do { _Pragma("unroll") for (int m = 0; m < 4; ++m) _Pragma("unroll") for (int k = 0; k < 2; ++k) dst[m][k] = *(const LAS bf16x8*)(lds + PG8_SA(b, h) + aoff + m * 2048 + k * 1024); } while (0)
; #define PG8_LDB(dst, b, h) do { _Pragma("unroll") for (int n = 0; n < 2; ++n) _Pragma("unroll") for (int k = 0; k < 2; ++k) dst[n][k] = *(const LAS bf16x8*)(lds + PG8_SB(b, h) + boff + n * 2048 + k * 1024); } while (0)
; #define PG8_MMA(ai, bj, At, Bt_) do { __builtin_amdgcn_s_setprio(1); _Pragma("unroll") for (int m = 0; m < 4; ++m) _Pragma("unroll") for (int n = 0; n < 2; ++n) _Pragma("unroll") for (int k = 0; k < 2; ++k) \
;     acc[ai][bj][m][n] = __builtin_amdgcn_mfma_f32_16x16x32_bf16(Bt_[n][k], At[m][k], acc[ai][bj][m][n], 0, 0, 0); __builtin_amdgcn_s_setprio(0); } while (0)
; #define PG8_WAIT_V(n) asm volatile("s_waitcnt vmcnt(" #n ")" ::: "memory")
; #define PG8_WAIT_L(n) asm volatile("s_waitcnt lgkmcnt(" #n ")" ::: "memory")
; #define PG8_BAR __builtin_amdgcn_s_barrier()
; #define PG8_SCHED __builtin_amdgcn_sched_barrier(0)
; template <int EPI>
; __device__ __forceinline__ void gemm_phase(KP P, const bfu* __restrict__ A, const bfu* __restrict__ Bt, int K, int ntn, char* smem, const int wv) {
;     ...
;     for (int t = 0; t < nt; t += 2) {
;       const bool last = (t == nt - 2);
;       const char* a1 = cA + (size_t)(t + 1) * kstep;
;       const char* a2 = last ? nA : cA + (size_t)(t + 2) * kstep;
;       const char* b2 = last ? nB : cB + (size_t)(t + 2) * kstep;
;       const char* a3 = a2 + kstep;
;       const char* b3 = b2 + kstep;
;       PG8_LDB(B0, 0, 0); PG8_SCHED; PG8_LDA(At, 0, 0); PG8_STAGE(PG8_SA(1, 1), a1 + hstep);
;       PG8_WAIT_L(8); PG8_BAR; PG8_WAIT_L(0); PG8_MMA(0, 0, At, B0); PG8_BAR; PG8_SCHED;
;       PG8_LDB(B1, 0, 1); PG8_STAGE(PG8_SB(0, 0), b2);
;       PG8_BAR; PG8_WAIT_L(0); PG8_MMA(0, 1, At, B1); PG8_BAR;
;       PG8_LDA(At, 0, 1); PG8_STAGE(PG8_SA(0, 0), a2);
;       PG8_BAR; PG8_WAIT_L(0); PG8_MMA(1, 0, At, B0); PG8_BAR; PG8_SCHED;
;       PG8_STAGE(PG8_SB(0, 1), b2 + hstep);
;       PG8_WAIT_V(6); PG8_BAR; PG8_MMA(1, 1, At, B1); PG8_BAR;
.LBB0_310:
	v_add_u32_e32 v0, s23, v145
	s_add_u32 s26, s76, s24
	ds_read_b128 v[150:153], v0
	ds_read_b128 v[154:157], v0 offset:1024
	ds_read_b128 v[158:161], v0 offset:2048
	ds_read_b128 v[180:183], v0 offset:3072
	s_addc_u32 s27, s77, s25
	s_add_u32 s26, s26, 0x11290100
	s_addc_u32 s27, s27, 0
	s_add_u32 s81, s78, s24
	s_addc_u32 s82, s79, s25
	s_cmpk_eq_i32 s24, 0xf00
	s_cselect_b32 s31, s21, s27
	s_cselect_b32 s30, s5, s26
	s_cselect_b32 s27, s75, s82
	s_cselect_b32 s26, s11, s81
	v_lshl_add_u64 v[162:163], v[138:139], 0, s[24:25]
	s_add_i32 m0, s41, 0xc000
	ds_read_b128 v[184:187], v149
	ds_read_b128 v[188:191], v149 offset:1024
	ds_read_b128 v[192:195], v149 offset:2048
	ds_read_b128 v[196:199], v149 offset:3072
	ds_read_b128 v[200:203], v149 offset:4096
	ds_read_b128 v[204:207], v149 offset:5120
	ds_read_b128 v[208:211], v149 offset:6144
	ds_read_b128 v[212:215], v149 offset:7168
	global_load_lds_dwordx4 v[162:163], off
	v_lshl_add_u64 v[162:163], v[140:141], 0, s[24:25]
	s_add_i32 m0, s41, 0xe000
	s_nop 0
	global_load_lds_dwordx4 v[162:163], off
	s_waitcnt lgkmcnt(8)
	s_barrier
	s_waitcnt lgkmcnt(0)
	s_setprio 1
	s_waitcnt lgkmcnt(0)
	v_mfma_f32_16x16x32_bf16 v[2:5], v[150:153], v[184:187], v[2:5]
	v_mfma_f32_16x16x32_bf16 v[6:9], v[158:161], v[184:187], v[6:9]
	v_mfma_f32_16x16x32_bf16 v[18:21], v[150:153], v[192:195], v[18:21]
	v_mfma_f32_16x16x32_bf16 v[22:25], v[158:161], v[192:195], v[22:25]
	v_mfma_f32_16x16x32_bf16 v[34:37], v[150:153], v[200:203], v[34:37]
	v_mfma_f32_16x16x32_bf16 v[38:41], v[158:161], v[200:203], v[38:41]
	v_mfma_f32_16x16x32_bf16 v[50:53], v[150:153], v[208:211], v[50:53]
	v_mfma_f32_16x16x32_bf16 v[54:57], v[158:161], v[208:211], v[54:57]
	v_mfma_f32_16x16x32_bf16 v[2:5], v[154:157], v[188:191], v[2:5]
	v_mfma_f32_16x16x32_bf16 v[6:9], v[180:183], v[188:191], v[6:9]
	v_mfma_f32_16x16x32_bf16 v[18:21], v[154:157], v[196:199], v[18:21]
	v_mfma_f32_16x16x32_bf16 v[22:25], v[180:183], v[196:199], v[22:25]
	v_mfma_f32_16x16x32_bf16 v[34:37], v[154:157], v[204:207], v[34:37]
	v_mfma_f32_16x16x32_bf16 v[38:41], v[180:183], v[204:207], v[38:41]
	v_mfma_f32_16x16x32_bf16 v[50:53], v[154:157], v[212:215], v[50:53]
	v_mfma_f32_16x16x32_bf16 v[54:57], v[180:183], v[212:215], v[54:57]
	s_setprio 0
	s_barrier
	s_mov_b32 m0, s39
	v_add_u32_e32 v0, s43, v145
	v_lshl_add_u64 v[162:163], s[26:27], 0, v[130:131]
	ds_read_b128 v[216:219], v0
	ds_read_b128 v[220:223], v0 offset:1024
	ds_read_b128 v[224:227], v0 offset:2048
	ds_read_b128 v[228:231], v0 offset:3072
	global_load_lds_dwordx4 v[162:163], off
	v_lshl_add_u64 v[232:233], s[26:27], 0, v[132:133]
	s_mov_b32 m0, s40
	s_nop 0
	global_load_lds_dwordx4 v[232:233], off
	s_barrier
	s_waitcnt lgkmcnt(0)
	s_setprio 1
	s_waitcnt lgkmcnt(0)
	v_mfma_f32_16x16x32_bf16 v[10:13], v[216:219], v[184:187], v[10:13]
	v_mfma_f32_16x16x32_bf16 v[14:17], v[224:227], v[184:187], v[14:17]
	v_mfma_f32_16x16x32_bf16 v[26:29], v[216:219], v[192:195], v[26:29]
	v_mfma_f32_16x16x32_bf16 v[30:33], v[224:227], v[192:195], v[30:33]
	v_mfma_f32_16x16x32_bf16 v[42:45], v[216:219], v[200:203], v[42:45]
	v_mfma_f32_16x16x32_bf16 v[46:49], v[224:227], v[200:203], v[46:49]
	v_mfma_f32_16x16x32_bf16 v[58:61], v[216:219], v[208:211], v[58:61]
	v_mfma_f32_16x16x32_bf16 v[62:65], v[224:227], v[208:211], v[62:65]
	v_mfma_f32_16x16x32_bf16 v[10:13], v[220:223], v[188:191], v[10:13]
	v_mfma_f32_16x16x32_bf16 v[14:17], v[228:231], v[188:191], v[14:17]
	v_mfma_f32_16x16x32_bf16 v[26:29], v[220:223], v[196:199], v[26:29]
	v_mfma_f32_16x16x32_bf16 v[30:33], v[228:231], v[196:199], v[30:33]
	v_mfma_f32_16x16x32_bf16 v[42:45], v[220:223], v[204:207], v[42:45]
	v_mfma_f32_16x16x32_bf16 v[46:49], v[228:231], v[204:207], v[46:49]
	v_mfma_f32_16x16x32_bf16 v[58:61], v[220:223], v[212:215], v[58:61]
	v_mfma_f32_16x16x32_bf16 v[62:65], v[228:231], v[212:215], v[62:65]
	s_setprio 0
	s_mov_b32 m0, s41
	v_lshl_add_u64 v[234:235], s[30:31], 0, v[130:131]
	s_barrier
	ds_read_b128 v[184:187], v149 offset:16384
	ds_read_b128 v[188:191], v149 offset:17408
	ds_read_b128 v[192:195], v149 offset:18432
	ds_read_b128 v[196:199], v149 offset:19456
	ds_read_b128 v[200:203], v149 offset:20480
	ds_read_b128 v[204:207], v149 offset:21504
	ds_read_b128 v[208:211], v149 offset:22528
	ds_read_b128 v[212:215], v149 offset:23552
	global_load_lds_dwordx4 v[234:235], off
	v_lshl_add_u64 v[236:237], s[30:31], 0, v[132:133]
	s_mov_b32 m0, s42
	s_nop 0
	global_load_lds_dwordx4 v[236:237], off
	s_barrier
	s_waitcnt lgkmcnt(0)
	s_setprio 1
	s_waitcnt lgkmcnt(0)
	v_mfma_f32_16x16x32_bf16 v[66:69], v[150:153], v[184:187], v[66:69]
	v_mfma_f32_16x16x32_bf16 v[70:73], v[158:161], v[184:187], v[70:73]
	v_mfma_f32_16x16x32_bf16 v[82:85], v[150:153], v[192:195], v[82:85]
	v_mfma_f32_16x16x32_bf16 v[86:89], v[158:161], v[192:195], v[86:89]
	v_mfma_f32_16x16x32_bf16 v[98:101], v[150:153], v[200:203], v[98:101]
	v_mfma_f32_16x16x32_bf16 v[102:105], v[158:161], v[200:203], v[102:105]
	v_mfma_f32_16x16x32_bf16 v[114:117], v[150:153], v[208:211], v[114:117]
	v_mfma_f32_16x16x32_bf16 v[118:121], v[158:161], v[208:211], v[118:121]
	v_mfma_f32_16x16x32_bf16 v[66:69], v[154:157], v[188:191], v[66:69]
	v_mfma_f32_16x16x32_bf16 v[70:73], v[180:183], v[188:191], v[70:73]
	v_mfma_f32_16x16x32_bf16 v[82:85], v[154:157], v[196:199], v[82:85]
	v_mfma_f32_16x16x32_bf16 v[86:89], v[180:183], v[196:199], v[86:89]
	v_mfma_f32_16x16x32_bf16 v[98:101], v[154:157], v[204:207], v[98:101]
	v_mfma_f32_16x16x32_bf16 v[102:105], v[180:183], v[204:207], v[102:105]
	v_mfma_f32_16x16x32_bf16 v[114:117], v[154:157], v[212:215], v[114:117]
	v_mfma_f32_16x16x32_bf16 v[118:121], v[180:183], v[212:215], v[118:121]
	s_setprio 0
	s_barrier
; #define PG8_STAGE(bufoff, gbase) do { _Pragma("unroll") for (int _i = 0; _i < 2; ++_i) \
;     __builtin_amdgcn_global_load_lds((const unsigned*)((const char*)(gbase) + voff[_i]), (LAS unsigned*)(lds + (bufoff) + ldsw + _i * 8192), 16, 0, 0); } while (0)
; #define PG8_LDA(dst, b, h) do { _Pragma("unroll") for (int m = 0; m < 4; ++m) _Pragma("unroll") for (int k = 0; k < 2; ++k) dst[m][k] = *(const LAS bf16x8*)(lds + PG8_SA(b, h) + aoff + m * 2048 + k * 1024); } while (0)
; #define PG8_LDB(dst, b, h) do { _Pragma("unroll") for (int n = 0; n < 2; ++n) _Pragma("unroll") for (int k = 0; k < 2; ++k) dst[n][k] = *(const LAS bf16x8*)(lds + PG8_SB(b, h) + boff + n * 2048 + k * 1024); } while (0)
; #define PG8_MMA(ai, bj, At, Bt_) do { __builtin_amdgcn_s_setprio(1); _Pragma("unroll") for (int m = 0; m < 4; ++m) _Pragma("unroll") for (int n = 0; n < 2; ++n) _Pragma("unroll") for (int k = 0; k < 2; ++k) \
;     acc[ai][bj][m][n] = __builtin_amdgcn_mfma_f32_16x16x32_bf16(Bt_[n][k], At[m][k], acc[ai][bj][m][n], 0, 0, 0); __builtin_amdgcn_s_setprio(0); } while (0)
; #define PG8_WAIT_V(n) asm volatile("s_waitcnt vmcnt(" #n ")" ::: "memory")
; #define PG8_WAIT_L(n) asm volatile("s_waitcnt lgkmcnt(" #n ")" ::: "memory")
; #define PG8_BAR __builtin_amdgcn_s_barrier()
; #define PG8_SCHED __builtin_amdgcn_sched_barrier(0)
; template <int EPI>
; __device__ __forceinline__ void gemm_phase(KP P, const bfu* __restrict__ A, const bfu* __restrict__ Bt, int K, int ntn, char* smem, const int wv) {
;     ...
;       PG8_STAGE(PG8_SB(0, 1), b2 + hstep);
;       PG8_WAIT_V(6); PG8_BAR; PG8_MMA(1, 1, At, B1); PG8_BAR;
;       PG8_LDB(B0, 1, 0); PG8_SCHED; PG8_LDA(At, 1, 0); PG8_STAGE(PG8_SA(0, 1), a2 + hstep);
;       PG8_WAIT_L(8); PG8_BAR; PG8_WAIT_L(0); PG8_MMA(0, 0, At, B0); PG8_BAR; PG8_SCHED;
;       PG8_LDB(B1, 1, 1); PG8_STAGE(PG8_SB(1, 0), b3);
;       PG8_BAR; PG8_WAIT_L(0); PG8_MMA(0, 1, At, B1); PG8_BAR;
;       PG8_LDA(At, 1, 1); PG8_STAGE(PG8_SA(1, 0), a3);
;       PG8_BAR; PG8_WAIT_L(0); PG8_MMA(1, 0, At, B0); PG8_BAR; PG8_SCHED;
	s_add_u32 s82, s26, 0x80000
	s_addc_u32 s83, s27, 0
	s_mov_b32 m0, s44
	v_lshl_add_u64 v[150:151], s[82:83], 0, v[130:131]
	global_load_lds_dwordx4 v[150:151], off
	v_lshl_add_u64 v[150:151], s[82:83], 0, v[132:133]
	s_mov_b32 m0, s45
	s_nop 0
	global_load_lds_dwordx4 v[150:151], off
	s_waitcnt vmcnt(6)
	s_barrier
	s_setprio 1
	v_mfma_f32_16x16x32_bf16 v[74:77], v[216:219], v[184:187], v[74:77]
	v_mfma_f32_16x16x32_bf16 v[78:81], v[224:227], v[184:187], v[78:81]
	v_mfma_f32_16x16x32_bf16 v[90:93], v[216:219], v[192:195], v[90:93]
	v_mfma_f32_16x16x32_bf16 v[94:97], v[224:227], v[192:195], v[94:97]
	v_mfma_f32_16x16x32_bf16 v[106:109], v[216:219], v[200:203], v[106:109]
	v_mfma_f32_16x16x32_bf16 v[110:113], v[224:227], v[200:203], v[110:113]
	v_mfma_f32_16x16x32_bf16 v[122:125], v[216:219], v[208:211], v[122:125]
	v_mfma_f32_16x16x32_bf16 v[126:129], v[224:227], v[208:211], v[126:129]
	v_mfma_f32_16x16x32_bf16 v[74:77], v[220:223], v[188:191], v[74:77]
	v_mfma_f32_16x16x32_bf16 v[78:81], v[228:231], v[188:191], v[78:81]
	v_mfma_f32_16x16x32_bf16 v[90:93], v[220:223], v[196:199], v[90:93]
	v_mfma_f32_16x16x32_bf16 v[94:97], v[228:231], v[196:199], v[94:97]
	v_mfma_f32_16x16x32_bf16 v[106:109], v[220:223], v[204:207], v[106:109]
	v_mfma_f32_16x16x32_bf16 v[110:113], v[228:231], v[204:207], v[110:113]
	v_mfma_f32_16x16x32_bf16 v[122:125], v[220:223], v[212:215], v[122:125]
	v_mfma_f32_16x16x32_bf16 v[126:129], v[228:231], v[212:215], v[126:129]
	s_setprio 0
	v_add_u32_e32 v0, s48, v145
	s_barrier
	ds_read_b128 v[150:153], v0
	ds_read_b128 v[154:157], v0 offset:1024
	ds_read_b128 v[158:161], v0 offset:2048
	ds_read_b128 v[180:183], v0 offset:3072
	s_add_u32 s30, s30, 0x80000
	s_addc_u32 s31, s31, 0
	s_mov_b32 m0, s46
	v_lshl_add_u64 v[216:217], s[30:31], 0, v[130:131]
	ds_read_b128 v[184:187], v149 offset:32768
	ds_read_b128 v[188:191], v149 offset:33792
	ds_read_b128 v[192:195], v149 offset:34816
	ds_read_b128 v[196:199], v149 offset:35840
	ds_read_b128 v[200:203], v149 offset:36864
	ds_read_b128 v[204:207], v149 offset:37888
	ds_read_b128 v[208:211], v149 offset:38912
	ds_read_b128 v[212:215], v149 offset:39936
	global_load_lds_dwordx4 v[216:217], off
	v_lshl_add_u64 v[216:217], s[30:31], 0, v[132:133]
	s_mov_b32 m0, s47
	s_nop 0
	global_load_lds_dwordx4 v[216:217], off
	s_waitcnt lgkmcnt(8)
	s_barrier
	s_waitcnt lgkmcnt(0)
	s_setprio 1
	s_waitcnt lgkmcnt(0)
	v_mfma_f32_16x16x32_bf16 v[2:5], v[150:153], v[184:187], v[2:5]
	v_mfma_f32_16x16x32_bf16 v[6:9], v[158:161], v[184:187], v[6:9]
	v_mfma_f32_16x16x32_bf16 v[18:21], v[150:153], v[192:195], v[18:21]
	v_mfma_f32_16x16x32_bf16 v[22:25], v[158:161], v[192:195], v[22:25]
	v_mfma_f32_16x16x32_bf16 v[34:37], v[150:153], v[200:203], v[34:37]
	v_mfma_f32_16x16x32_bf16 v[38:41], v[158:161], v[200:203], v[38:41]
	v_mfma_f32_16x16x32_bf16 v[50:53], v[150:153], v[208:211], v[50:53]
	v_mfma_f32_16x16x32_bf16 v[54:57], v[158:161], v[208:211], v[54:57]
	v_mfma_f32_16x16x32_bf16 v[2:5], v[154:157], v[188:191], v[2:5]
	v_mfma_f32_16x16x32_bf16 v[6:9], v[180:183], v[188:191], v[6:9]
	v_mfma_f32_16x16x32_bf16 v[18:21], v[154:157], v[196:199], v[18:21]
	v_mfma_f32_16x16x32_bf16 v[22:25], v[180:183], v[196:199], v[22:25]
	v_mfma_f32_16x16x32_bf16 v[34:37], v[154:157], v[204:207], v[34:37]
	v_mfma_f32_16x16x32_bf16 v[38:41], v[180:183], v[204:207], v[38:41]
	v_mfma_f32_16x16x32_bf16 v[50:53], v[154:157], v[212:215], v[50:53]
	v_mfma_f32_16x16x32_bf16 v[54:57], v[180:183], v[212:215], v[54:57]
	s_setprio 0
	s_barrier
	s_mov_b32 m0, s49
	v_add_u32_e32 v0, s60, v145
	v_lshl_add_u64 v[162:163], v[162:163], 0, s[90:91]
	ds_read_b128 v[216:219], v0
	ds_read_b128 v[220:223], v0 offset:1024
	ds_read_b128 v[224:227], v0 offset:2048
	ds_read_b128 v[228:231], v0 offset:3072
	global_load_lds_dwordx4 v[162:163], off
	v_lshl_add_u64 v[162:163], v[232:233], 0, s[90:91]
	s_mov_b32 m0, s50
	s_nop 0
	global_load_lds_dwordx4 v[162:163], off
	s_barrier
	s_waitcnt lgkmcnt(0)
	s_setprio 1
	s_waitcnt lgkmcnt(0)
	v_mfma_f32_16x16x32_bf16 v[10:13], v[216:219], v[184:187], v[10:13]
	v_mfma_f32_16x16x32_bf16 v[14:17], v[224:227], v[184:187], v[14:17]
	v_mfma_f32_16x16x32_bf16 v[26:29], v[216:219], v[192:195], v[26:29]
	v_mfma_f32_16x16x32_bf16 v[30:33], v[224:227], v[192:195], v[30:33]
	v_mfma_f32_16x16x32_bf16 v[42:45], v[216:219], v[200:203], v[42:45]
	v_mfma_f32_16x16x32_bf16 v[46:49], v[224:227], v[200:203], v[46:49]
	v_mfma_f32_16x16x32_bf16 v[58:61], v[216:219], v[208:211], v[58:61]
	v_mfma_f32_16x16x32_bf16 v[62:65], v[224:227], v[208:211], v[62:65]
	v_mfma_f32_16x16x32_bf16 v[10:13], v[220:223], v[188:191], v[10:13]
	v_mfma_f32_16x16x32_bf16 v[14:17], v[228:231], v[188:191], v[14:17]
	v_mfma_f32_16x16x32_bf16 v[26:29], v[220:223], v[196:199], v[26:29]
	v_mfma_f32_16x16x32_bf16 v[30:33], v[228:231], v[196:199], v[30:33]
	v_mfma_f32_16x16x32_bf16 v[42:45], v[220:223], v[204:207], v[42:45]
	v_mfma_f32_16x16x32_bf16 v[46:49], v[228:231], v[204:207], v[46:49]
	v_mfma_f32_16x16x32_bf16 v[58:61], v[220:223], v[212:215], v[58:61]
	v_mfma_f32_16x16x32_bf16 v[62:65], v[228:231], v[212:215], v[62:65]
	s_setprio 0
	s_mov_b32 m0, s51
	v_lshl_add_u64 v[162:163], v[234:235], 0, s[90:91]
	s_barrier
	ds_read_b128 v[184:187], v149 offset:49152
	ds_read_b128 v[188:191], v149 offset:50176
	ds_read_b128 v[192:195], v149 offset:51200
	ds_read_b128 v[196:199], v149 offset:52224
	ds_read_b128 v[200:203], v149 offset:53248
	ds_read_b128 v[204:207], v149 offset:54272
	ds_read_b128 v[208:211], v149 offset:55296
	ds_read_b128 v[212:215], v149 offset:56320
	global_load_lds_dwordx4 v[162:163], off
	v_lshl_add_u64 v[162:163], v[236:237], 0, s[90:91]
	s_mov_b32 m0, s52
	s_nop 0
	global_load_lds_dwordx4 v[162:163], off
	s_barrier
; #define PG8_STAGE(bufoff, gbase) do { _Pragma("unroll") for (int _i = 0; _i < 2; ++_i) \
;     __builtin_amdgcn_global_load_lds((const unsigned*)((const char*)(gbase) + voff[_i]), (LAS unsigned*)(lds + (bufoff) + ldsw + _i * 8192), 16, 0, 0); } while (0)
; #define PG8_MMA(ai, bj, At, Bt_) do { __builtin_amdgcn_s_setprio(1); _Pragma("unroll") for (int m = 0; m < 4; ++m) _Pragma("unroll") for (int n = 0; n < 2; ++n) _Pragma("unroll") for (int k = 0; k < 2; ++k) \
;     acc[ai][bj][m][n] = __builtin_amdgcn_mfma_f32_16x16x32_bf16(Bt_[n][k], At[m][k], acc[ai][bj][m][n], 0, 0, 0); __builtin_amdgcn_s_setprio(0); } while (0)
; #define PG8_WAIT_V(n) asm volatile("s_waitcnt vmcnt(" #n ")" ::: "memory")
; #define PG8_WAIT_L(n) asm volatile("s_waitcnt lgkmcnt(" #n ")" ::: "memory")
; #define PG8_BAR __builtin_amdgcn_s_barrier()
; #define PG8_SCHED __builtin_amdgcn_sched_barrier(0)
; template <int EPI>
; __device__ __forceinline__ void gemm_epilogue(KP P, f32x4 (&acc)[2][2][4][2], int brow, int bcol, int wr, int wc, int fr_, int fq_, const float* sRu) {
;     ...
;   } else if (EPI == EPI_OUTPROJ || EPI == EPI_RES) {
;     bfu* xo = (bfu*)(P->ws + WS_XR) + (size_t)brow * D + bcol;
; #pragma unroll
;     for (int ai = 0; ai < 2; ++ai)
; #pragma unroll
;       for (int m = 0; m < 4; ++m) {
;         __builtin_amdgcn_sched_barrier(0);
;         unsigned lr = lrow0 + ai * 128 + m * 16;
;         unsigned o = lr * D + lcol0;
;         float rsd = 1.f;
;         if (EPI == EPI_OUTPROJ) rsd = sRu[lr];
; #pragma unroll
;         for (int bj = 0; bj < 2; ++bj)
; #pragma unroll
;           for (int n = 0; n < 2; ++n) {
;             f32x4 v = acc[ai][bj][m][n] * rsd;
;             uint2 pk; pk.x = cvt_pk_bf16(v[0], v[1]); pk.y = cvt_pk_bf16(v[2], v[3]);
;             *(uint2*)(xo + o + bj * 128 + n * 16) = pk;
;           }
;       }
; template <int EPI>
; __device__ __forceinline__ void gemm_phase(KP P, const bfu* __restrict__ A, const bfu* __restrict__ Bt, int K, int ntn, char* smem, const int wv) {
;     ...
;       PG8_BAR; PG8_WAIT_L(0); PG8_MMA(1, 0, At, B0); PG8_BAR; PG8_SCHED;
;       PG8_STAGE(PG8_SB(1, 1), b3 + hstep);
;       PG8_WAIT_V(6); PG8_BAR; PG8_MMA(1, 1, At, B1); PG8_BAR;
;     }
	s_waitcnt lgkmcnt(0)
	s_setprio 1
	s_waitcnt lgkmcnt(0)
	v_mfma_f32_16x16x32_bf16 v[66:69], v[150:153], v[184:187], v[66:69]
	v_mfma_f32_16x16x32_bf16 v[70:73], v[158:161], v[184:187], v[70:73]
	v_mfma_f32_16x16x32_bf16 v[82:85], v[150:153], v[192:195], v[82:85]
	v_mfma_f32_16x16x32_bf16 v[86:89], v[158:161], v[192:195], v[86:89]
	v_mfma_f32_16x16x32_bf16 v[98:101], v[150:153], v[200:203], v[98:101]
	v_mfma_f32_16x16x32_bf16 v[102:105], v[158:161], v[200:203], v[102:105]
	v_mfma_f32_16x16x32_bf16 v[114:117], v[150:153], v[208:211], v[114:117]
	v_mfma_f32_16x16x32_bf16 v[118:121], v[158:161], v[208:211], v[118:121]
	v_mfma_f32_16x16x32_bf16 v[66:69], v[154:157], v[188:191], v[66:69]
	v_mfma_f32_16x16x32_bf16 v[70:73], v[180:183], v[188:191], v[70:73]
	v_mfma_f32_16x16x32_bf16 v[82:85], v[154:157], v[196:199], v[82:85]
	v_mfma_f32_16x16x32_bf16 v[86:89], v[180:183], v[196:199], v[86:89]
	v_mfma_f32_16x16x32_bf16 v[98:101], v[154:157], v[204:207], v[98:101]
	v_mfma_f32_16x16x32_bf16 v[102:105], v[180:183], v[204:207], v[102:105]
	v_mfma_f32_16x16x32_bf16 v[114:117], v[154:157], v[212:215], v[114:117]
	v_mfma_f32_16x16x32_bf16 v[118:121], v[180:183], v[212:215], v[118:121]
	s_setprio 0
	s_barrier
	s_add_u32 s26, s26, 0x80080
	s_addc_u32 s27, s27, 0
	s_mov_b32 m0, s62
	v_lshl_add_u64 v[150:151], s[26:27], 0, v[130:131]
	global_load_lds_dwordx4 v[150:151], off
	v_lshl_add_u64 v[150:151], s[26:27], 0, v[132:133]
	s_mov_b32 m0, s67
	s_nop 0
	global_load_lds_dwordx4 v[150:151], off
	s_waitcnt vmcnt(6)
	s_barrier
	s_setprio 1
	v_mfma_f32_16x16x32_bf16 v[74:77], v[216:219], v[184:187], v[74:77]
	v_mfma_f32_16x16x32_bf16 v[78:81], v[224:227], v[184:187], v[78:81]
	v_mfma_f32_16x16x32_bf16 v[90:93], v[216:219], v[192:195], v[90:93]
	v_mfma_f32_16x16x32_bf16 v[94:97], v[224:227], v[192:195], v[94:97]
	v_mfma_f32_16x16x32_bf16 v[106:109], v[216:219], v[200:203], v[106:109]
	v_mfma_f32_16x16x32_bf16 v[110:113], v[224:227], v[200:203], v[110:113]
	v_mfma_f32_16x16x32_bf16 v[122:125], v[216:219], v[208:211], v[122:125]
	v_mfma_f32_16x16x32_bf16 v[126:129], v[224:227], v[208:211], v[126:129]
	v_mfma_f32_16x16x32_bf16 v[74:77], v[220:223], v[188:191], v[74:77]
	v_mfma_f32_16x16x32_bf16 v[78:81], v[228:231], v[188:191], v[78:81]
	v_mfma_f32_16x16x32_bf16 v[90:93], v[220:223], v[196:199], v[90:93]
	v_mfma_f32_16x16x32_bf16 v[94:97], v[228:231], v[196:199], v[94:97]
	v_mfma_f32_16x16x32_bf16 v[106:109], v[220:223], v[204:207], v[106:109]
	v_mfma_f32_16x16x32_bf16 v[110:113], v[228:231], v[204:207], v[110:113]
	v_mfma_f32_16x16x32_bf16 v[122:125], v[220:223], v[212:215], v[122:125]
	v_mfma_f32_16x16x32_bf16 v[126:129], v[228:231], v[212:215], v[126:129]
	s_setprio 0
	s_add_i32 s80, s80, 2
	s_add_u32 s24, s24, 0x100
	s_addc_u32 s25, s25, 0
	s_cmp_gt_u32 s80, 29
	s_barrier
	s_cbranch_scc0 .LBB0_310
	s_lshl_b32 s24, s22, 8
	s_ashr_i32 s25, s24, 31
	s_lshl_b32 s20, s20, 8
	s_lshl_b64 s[24:25], s[24:25], 11
	s_add_u32 s5, s6, s24
	s_addc_u32 s11, s7, s25
	s_ashr_i32 s21, s20, 31
	s_lshl_b64 s[20:21], s[20:21], 1
	v_mov_b32_e32 v0, v142
	v_mov_b32_e32 v138, v143
	s_add_u32 s20, s5, s20
	s_addc_u32 s21, s11, s21
	v_add_u32_e32 v0, s94, v0
	v_lshlrev_b32_e32 v139, 2, v138
	v_lshl_add_u32 v150, v0, 2, s74
	ds_read_b32 v138, v150
	v_lshlrev_b32_e32 v0, 10, v0
	v_readlane_b32 s5, v241, 20
	s_waitcnt lgkmcnt(0)
	v_pk_mul_f32 v[4:5], v[4:5], v[138:139] op_sel_hi:[1,0]
	v_add3_u32 v0, v139, s5, v0
	v_and_b32_e32 v208, 1, v143
	v_mul_u32_u24_e32 v208, 12, v208
	v_add_u32_e32 v0, v0, v208
	v_pk_mul_f32 v[2:3], v[2:3], v[138:139] op_sel_hi:[1,0]
	v_lshl_add_u64 v[140:141], v[0:1], 1, s[20:21]
	v_cvt_pk_bf16_f32 v200, v2, v3
	v_cvt_pk_bf16_f32 v201, v4, v5
	v_pk_mul_f32 v[4:5], v[6:7], v[138:139] op_sel_hi:[1,0]
	v_pk_mul_f32 v[2:3], v[8:9], v[138:139] op_sel_hi:[1,0]
	v_cvt_pk_bf16_f32 v202, v4, v5
	s_nop 0
	v_cvt_pk_bf16_f32 v203, v2, v3
	s_nop 1
	v_permlane16_swap_b32_e32 v200, v202
	v_permlane16_swap_b32_e32 v201, v203
	global_store_dwordx4 v[140:141], v[200:203], off
	v_pk_mul_f32 v[4:5], v[10:11], v[138:139] op_sel_hi:[1,0]
	v_pk_mul_f32 v[2:3], v[12:13], v[138:139] op_sel_hi:[1,0]
	v_cvt_pk_bf16_f32 v204, v4, v5
	s_nop 0
	v_cvt_pk_bf16_f32 v205, v2, v3
	v_pk_mul_f32 v[2:3], v[16:17], v[138:139] op_sel_hi:[1,0]
	v_pk_mul_f32 v[4:5], v[14:15], v[138:139] op_sel_hi:[1,0]
	s_nop 0
	v_cvt_pk_bf16_f32 v206, v4, v5
	v_cvt_pk_bf16_f32 v207, v2, v3
	s_nop 1
	v_permlane16_swap_b32_e32 v204, v206
	v_permlane16_swap_b32_e32 v205, v207
	global_store_dwordx4 v[140:141], v[204:207], off offset:256
	ds_read_b32 v2, v150 offset:64
	v_add_u32_e32 v4, 0x4000, v0
	v_mov_b32_e32 v5, v1
	v_lshl_add_u64 v[4:5], v[4:5], 1, s[20:21]
	s_waitcnt lgkmcnt(0)
	v_pk_mul_f32 v[8:9], v[18:19], v[2:3] op_sel_hi:[1,0]
	v_pk_mul_f32 v[6:7], v[20:21], v[2:3] op_sel_hi:[1,0]
	v_cvt_pk_bf16_f32 v200, v8, v9
	s_nop 0
	v_cvt_pk_bf16_f32 v201, v6, v7
	v_pk_mul_f32 v[8:9], v[22:23], v[2:3] op_sel_hi:[1,0]
	v_pk_mul_f32 v[6:7], v[24:25], v[2:3] op_sel_hi:[1,0]
	v_cvt_pk_bf16_f32 v202, v8, v9
	s_nop 0
	v_cvt_pk_bf16_f32 v203, v6, v7
	s_nop 1
	v_permlane16_swap_b32_e32 v200, v202
	v_permlane16_swap_b32_e32 v201, v203
	global_store_dwordx4 v[4:5], v[200:203], off
	v_pk_mul_f32 v[6:7], v[28:29], v[2:3] op_sel_hi:[1,0]
	v_pk_mul_f32 v[8:9], v[26:27], v[2:3] op_sel_hi:[1,0]
	s_nop 0
	v_cvt_pk_bf16_f32 v204, v8, v9
	v_cvt_pk_bf16_f32 v205, v6, v7
	v_pk_mul_f32 v[6:7], v[32:33], v[2:3] op_sel_hi:[1,0]
	v_pk_mul_f32 v[2:3], v[30:31], v[2:3] op_sel_hi:[1,0]
	v_cvt_pk_bf16_f32 v206, v2, v3
	v_cvt_pk_bf16_f32 v207, v6, v7
	s_nop 1
	v_permlane16_swap_b32_e32 v204, v206
	v_permlane16_swap_b32_e32 v205, v207
	global_store_dwordx4 v[4:5], v[204:207], off offset:256
	ds_read_b32 v2, v150 offset:128
	v_add_u32_e32 v4, 0x8000, v0
	v_mov_b32_e32 v5, v1
	v_lshl_add_u64 v[4:5], v[4:5], 1, s[20:21]
	s_waitcnt lgkmcnt(0)
; template <int EPI>
; __device__ __forceinline__ void gemm_epilogue(KP P, f32x4 (&acc)[2][2][4][2], int brow, int bcol, int wr, int wc, int fr_, int fq_, const float* sRu) {
;     ...
;   } else if (EPI == EPI_OUTPROJ || EPI == EPI_RES) {
;     bfu* xo = (bfu*)(P->ws + WS_XR) + (size_t)brow * D + bcol;
; #pragma unroll
;     for (int ai = 0; ai < 2; ++ai)
; #pragma unroll
;       for (int m = 0; m < 4; ++m) {
;         __builtin_amdgcn_sched_barrier(0);
;         unsigned lr = lrow0 + ai * 128 + m * 16;
;         unsigned o = lr * D + lcol0;
;         float rsd = 1.f;
;         if (EPI == EPI_OUTPROJ) rsd = sRu[lr];
; #pragma unroll
;         for (int bj = 0; bj < 2; ++bj)
; #pragma unroll
;           for (int n = 0; n < 2; ++n) {
;             f32x4 v = acc[ai][bj][m][n] * rsd;
;             uint2 pk; pk.x = cvt_pk_bf16(v[0], v[1]); pk.y = cvt_pk_bf16(v[2], v[3]);
;             *(uint2*)(xo + o + bj * 128 + n * 16) = pk;
;           }
;       }
	v_pk_mul_f32 v[8:9], v[34:35], v[2:3] op_sel_hi:[1,0]
	v_pk_mul_f32 v[6:7], v[36:37], v[2:3] op_sel_hi:[1,0]
	v_cvt_pk_bf16_f32 v200, v8, v9
	s_nop 0
	v_cvt_pk_bf16_f32 v201, v6, v7
	v_pk_mul_f32 v[8:9], v[38:39], v[2:3] op_sel_hi:[1,0]
	v_pk_mul_f32 v[6:7], v[40:41], v[2:3] op_sel_hi:[1,0]
	v_cvt_pk_bf16_f32 v202, v8, v9
	s_nop 0
	v_cvt_pk_bf16_f32 v203, v6, v7
	s_nop 1
	v_permlane16_swap_b32_e32 v200, v202
	v_permlane16_swap_b32_e32 v201, v203
	global_store_dwordx4 v[4:5], v[200:203], off
	v_pk_mul_f32 v[6:7], v[44:45], v[2:3] op_sel_hi:[1,0]
	v_pk_mul_f32 v[8:9], v[42:43], v[2:3] op_sel_hi:[1,0]
	s_nop 0
	v_cvt_pk_bf16_f32 v204, v8, v9
	v_cvt_pk_bf16_f32 v205, v6, v7
	v_pk_mul_f32 v[6:7], v[48:49], v[2:3] op_sel_hi:[1,0]
	v_pk_mul_f32 v[2:3], v[46:47], v[2:3] op_sel_hi:[1,0]
	v_cvt_pk_bf16_f32 v206, v2, v3
	v_cvt_pk_bf16_f32 v207, v6, v7
	s_nop 1
	v_permlane16_swap_b32_e32 v204, v206
	v_permlane16_swap_b32_e32 v205, v207
	global_store_dwordx4 v[4:5], v[204:207], off offset:256
	ds_read_b32 v2, v150 offset:192
	v_add_u32_e32 v4, 0xc000, v0
	v_mov_b32_e32 v5, v1
	v_lshl_add_u64 v[4:5], v[4:5], 1, s[20:21]
	s_waitcnt lgkmcnt(0)
	v_pk_mul_f32 v[8:9], v[50:51], v[2:3] op_sel_hi:[1,0]
	v_pk_mul_f32 v[6:7], v[52:53], v[2:3] op_sel_hi:[1,0]
	v_cvt_pk_bf16_f32 v200, v8, v9
	s_nop 0
	v_cvt_pk_bf16_f32 v201, v6, v7
	v_pk_mul_f32 v[8:9], v[54:55], v[2:3] op_sel_hi:[1,0]
	v_pk_mul_f32 v[6:7], v[56:57], v[2:3] op_sel_hi:[1,0]
	v_cvt_pk_bf16_f32 v202, v8, v9
	s_nop 0
	v_cvt_pk_bf16_f32 v203, v6, v7
	s_nop 1
	v_permlane16_swap_b32_e32 v200, v202
	v_permlane16_swap_b32_e32 v201, v203
	global_store_dwordx4 v[4:5], v[200:203], off
	v_pk_mul_f32 v[6:7], v[60:61], v[2:3] op_sel_hi:[1,0]
	v_pk_mul_f32 v[8:9], v[58:59], v[2:3] op_sel_hi:[1,0]
	s_nop 0
	v_cvt_pk_bf16_f32 v204, v8, v9
	v_cvt_pk_bf16_f32 v205, v6, v7
	v_pk_mul_f32 v[6:7], v[64:65], v[2:3] op_sel_hi:[1,0]
	v_pk_mul_f32 v[2:3], v[62:63], v[2:3] op_sel_hi:[1,0]
	v_cvt_pk_bf16_f32 v206, v2, v3
	v_cvt_pk_bf16_f32 v207, v6, v7
	s_nop 1
	v_permlane16_swap_b32_e32 v204, v206
	v_permlane16_swap_b32_e32 v205, v207
	global_store_dwordx4 v[4:5], v[204:207], off offset:256
	ds_read_b32 v2, v150 offset:512
	v_add_u32_e32 v4, 0x20000, v0
	v_mov_b32_e32 v5, v1
	v_lshl_add_u64 v[4:5], v[4:5], 1, s[20:21]
	s_waitcnt lgkmcnt(0)
	v_pk_mul_f32 v[8:9], v[66:67], v[2:3] op_sel_hi:[1,0]
	v_pk_mul_f32 v[6:7], v[68:69], v[2:3] op_sel_hi:[1,0]
	v_cvt_pk_bf16_f32 v200, v8, v9
	s_nop 0
	v_cvt_pk_bf16_f32 v201, v6, v7
	v_pk_mul_f32 v[8:9], v[70:71], v[2:3] op_sel_hi:[1,0]
	v_pk_mul_f32 v[6:7], v[72:73], v[2:3] op_sel_hi:[1,0]
	v_cvt_pk_bf16_f32 v202, v8, v9
	s_nop 0
	v_cvt_pk_bf16_f32 v203, v6, v7
	s_nop 1
	v_permlane16_swap_b32_e32 v200, v202
	v_permlane16_swap_b32_e32 v201, v203
	global_store_dwordx4 v[4:5], v[200:203], off
	v_pk_mul_f32 v[6:7], v[76:77], v[2:3] op_sel_hi:[1,0]
	v_pk_mul_f32 v[8:9], v[74:75], v[2:3] op_sel_hi:[1,0]
	s_nop 0
	v_cvt_pk_bf16_f32 v204, v8, v9
	v_cvt_pk_bf16_f32 v205, v6, v7
	v_pk_mul_f32 v[6:7], v[80:81], v[2:3] op_sel_hi:[1,0]
	v_pk_mul_f32 v[2:3], v[78:79], v[2:3] op_sel_hi:[1,0]
	v_cvt_pk_bf16_f32 v206, v2, v3
	v_cvt_pk_bf16_f32 v207, v6, v7
	s_nop 1
	v_permlane16_swap_b32_e32 v204, v206
	v_permlane16_swap_b32_e32 v205, v207
	global_store_dwordx4 v[4:5], v[204:207], off offset:256
	ds_read_b32 v2, v150 offset:576
	v_add_u32_e32 v4, 0x24000, v0
	v_mov_b32_e32 v5, v1
	v_lshl_add_u64 v[4:5], v[4:5], 1, s[20:21]
	s_waitcnt lgkmcnt(0)
	v_pk_mul_f32 v[8:9], v[82:83], v[2:3] op_sel_hi:[1,0]
	v_pk_mul_f32 v[6:7], v[84:85], v[2:3] op_sel_hi:[1,0]
	v_cvt_pk_bf16_f32 v200, v8, v9
	s_nop 0
	v_cvt_pk_bf16_f32 v201, v6, v7
	v_pk_mul_f32 v[8:9], v[86:87], v[2:3] op_sel_hi:[1,0]
	v_pk_mul_f32 v[6:7], v[88:89], v[2:3] op_sel_hi:[1,0]
	v_cvt_pk_bf16_f32 v202, v8, v9
	s_nop 0
	v_cvt_pk_bf16_f32 v203, v6, v7
	s_nop 1
	v_permlane16_swap_b32_e32 v200, v202
	v_permlane16_swap_b32_e32 v201, v203
	global_store_dwordx4 v[4:5], v[200:203], off
	v_pk_mul_f32 v[6:7], v[92:93], v[2:3] op_sel_hi:[1,0]
	v_pk_mul_f32 v[8:9], v[90:91], v[2:3] op_sel_hi:[1,0]
	s_nop 0
	v_cvt_pk_bf16_f32 v204, v8, v9
	v_cvt_pk_bf16_f32 v205, v6, v7
	v_pk_mul_f32 v[6:7], v[96:97], v[2:3] op_sel_hi:[1,0]
	v_pk_mul_f32 v[2:3], v[94:95], v[2:3] op_sel_hi:[1,0]
	v_cvt_pk_bf16_f32 v206, v2, v3
	v_cvt_pk_bf16_f32 v207, v6, v7
	s_nop 1
	v_permlane16_swap_b32_e32 v204, v206
	v_permlane16_swap_b32_e32 v205, v207
	global_store_dwordx4 v[4:5], v[204:207], off offset:256
	ds_read_b32 v2, v150 offset:640
	v_add_u32_e32 v4, 0x28000, v0
	v_mov_b32_e32 v5, v1
	v_lshl_add_u64 v[4:5], v[4:5], 1, s[20:21]
	s_waitcnt lgkmcnt(0)
	v_pk_mul_f32 v[8:9], v[98:99], v[2:3] op_sel_hi:[1,0]
	v_pk_mul_f32 v[6:7], v[100:101], v[2:3] op_sel_hi:[1,0]
	v_cvt_pk_bf16_f32 v200, v8, v9
	s_nop 0
	v_cvt_pk_bf16_f32 v201, v6, v7
	v_pk_mul_f32 v[8:9], v[102:103], v[2:3] op_sel_hi:[1,0]
	v_pk_mul_f32 v[6:7], v[104:105], v[2:3] op_sel_hi:[1,0]
	v_cvt_pk_bf16_f32 v202, v8, v9
	s_nop 0
	v_cvt_pk_bf16_f32 v203, v6, v7
	s_nop 1
	v_permlane16_swap_b32_e32 v200, v202
	v_permlane16_swap_b32_e32 v201, v203
	global_store_dwordx4 v[4:5], v[200:203], off
	v_pk_mul_f32 v[6:7], v[108:109], v[2:3] op_sel_hi:[1,0]
	v_pk_mul_f32 v[8:9], v[106:107], v[2:3] op_sel_hi:[1,0]
	s_nop 0
	v_cvt_pk_bf16_f32 v204, v8, v9
	v_cvt_pk_bf16_f32 v205, v6, v7
	v_pk_mul_f32 v[6:7], v[112:113], v[2:3] op_sel_hi:[1,0]
	v_pk_mul_f32 v[2:3], v[110:111], v[2:3] op_sel_hi:[1,0]
	v_cvt_pk_bf16_f32 v206, v2, v3
	v_cvt_pk_bf16_f32 v207, v6, v7
	s_nop 1
	v_permlane16_swap_b32_e32 v204, v206
	v_permlane16_swap_b32_e32 v205, v207
	global_store_dwordx4 v[4:5], v[204:207], off offset:256
	ds_read_b32 v2, v150 offset:704
	v_add_u32_e32 v0, 0x2c000, v0
	v_lshl_add_u64 v[4:5], v[0:1], 1, s[20:21]
	s_mov_b64 s[20:21], -1
	s_and_b64 vcc, exec, s[28:29]
	s_waitcnt lgkmcnt(0)
	v_pk_mul_f32 v[8:9], v[114:115], v[2:3] op_sel_hi:[1,0]
	v_pk_mul_f32 v[6:7], v[116:117], v[2:3] op_sel_hi:[1,0]
	v_cvt_pk_bf16_f32 v200, v8, v9
	s_nop 0
	v_cvt_pk_bf16_f32 v201, v6, v7
	v_pk_mul_f32 v[8:9], v[118:119], v[2:3] op_sel_hi:[1,0]
	v_pk_mul_f32 v[6:7], v[120:121], v[2:3] op_sel_hi:[1,0]
	v_cvt_pk_bf16_f32 v202, v8, v9
	s_nop 0
	v_cvt_pk_bf16_f32 v203, v6, v7
	s_nop 1
	v_permlane16_swap_b32_e32 v200, v202
	v_permlane16_swap_b32_e32 v201, v203
	global_store_dwordx4 v[4:5], v[200:203], off
	v_pk_mul_f32 v[6:7], v[124:125], v[2:3] op_sel_hi:[1,0]
	v_pk_mul_f32 v[8:9], v[122:123], v[2:3] op_sel_hi:[1,0]
	s_nop 0
	v_cvt_pk_bf16_f32 v204, v8, v9
	v_cvt_pk_bf16_f32 v205, v6, v7
	v_pk_mul_f32 v[6:7], v[128:129], v[2:3] op_sel_hi:[1,0]
	v_pk_mul_f32 v[2:3], v[126:127], v[2:3] op_sel_hi:[1,0]
	v_cvt_pk_bf16_f32 v206, v2, v3
	v_cvt_pk_bf16_f32 v207, v6, v7
	s_nop 1
	v_permlane16_swap_b32_e32 v204, v206
	v_permlane16_swap_b32_e32 v205, v207
	global_store_dwordx4 v[4:5], v[204:207], off offset:256
	s_cbranch_vccz .LBB0_306
; template <int EPI>
; __device__ __forceinline__ void gemm_acc_init(KP P, f32x4 (&acc)[2][2][4][2], int brow, int bcol, int wr, int wc, int fr_, int fq_, const float* sRu) {
;   if (EPI == EPI_OUTPROJ || EPI == EPI_RES) {
;     int fr = fr_, fq = fq_;
;     asm volatile("" : "+v"(fr), "+v"(fq));
;     const float* xin = (brow < MP ? P->in[0] + (size_t)brow * D : P->in[1] + (size_t)(brow - MP) * D) + bcol;
;     const bfu* xrb = (const bfu*)(P->ws + WS_XR) + (size_t)brow * D + bcol;
; #pragma unroll
;     for (int ai = 0; ai < 2; ++ai)
; #pragma unroll
;       for (int m = 0; m < 4; ++m) {
;         __builtin_amdgcn_sched_barrier(0);
;         unsigned lr = ai * 128 + wr * 64 + m * 16 + fr;
;         unsigned o = lr * D + wc * 32 + fq * 4;
;         float sc = 1.f;
;         if (EPI == EPI_OUTPROJ) sc = 1.f / sRu[lr];
; #pragma unroll
;         for (int bj = 0; bj < 2; ++bj)
; #pragma unroll
;           for (int n = 0; n < 2; ++n) {
;             if (EPI == EPI_RES) acc[ai][bj][m][n] = bf4_to_f32(*(const uint2*)(xrb + o + bj * 128 + n * 16));
;             else acc[ai][bj][m][n] = *(const f32x4*)(xin + o + bj * 128 + n * 16) * sc;
;           }
;       }
	s_lshl_b32 s11, s4, 8
	s_add_i32 s5, s74, 0x400
	s_lshl_b32 s20, s10, 8
	s_add_i32 s21, s11, 0xffff0000
	s_ashr_i32 s22, s11, 31
	s_cmpk_lt_i32 s4, 0x100
	s_cselect_b32 s24, s11, s21
	s_cselect_b32 s11, 0, 8
	s_cselect_b32 s25, s22, 0
	s_add_u32 s26, s0, s11
	v_mov_b32_e32 v0, v143
	v_mov_b32_e32 v2, v142
	s_addc_u32 s27, s1, 0
	s_load_dwordx2 s[26:27], s[26:27], 0x0
	s_lshl_b64 s[24:25], s[24:25], 12
	v_add_u32_e32 v2, s94, v2
	v_lshlrev_b32_e32 v0, 2, v0
	s_waitcnt lgkmcnt(0)
	s_add_u32 s11, s26, s24
	s_addc_u32 s22, s27, s25
	s_ashr_i32 s21, s20, 31
	s_lshl_b64 s[20:21], s[20:21], 2
	s_add_u32 s20, s11, s20
	s_addc_u32 s21, s22, s21
	v_lshl_add_u32 v114, v2, 2, s74
	v_lshlrev_b32_e32 v3, 10, v2
	ds_read_b32 v2, v114 offset:1024
	v_readlane_b32 s11, v241, 20
	s_nop 1
	v_add3_u32 v0, v0, s11, v3
	s_waitcnt lgkmcnt(0)
	v_div_scale_f32 v3, s[24:25], v2, v2, 1.0
	v_rcp_f32_e32 v4, v3
	v_lshl_add_u64 v[14:15], v[0:1], 2, s[20:21]
	global_load_dwordx4 v[10:13], v[14:15], off offset:512
	v_fma_f32 v5, -v3, v4, 1.0
	v_fmac_f32_e32 v4, v5, v4
	v_div_scale_f32 v5, vcc, 1.0, v2, 1.0
	v_mul_f32_e32 v6, v5, v4
	v_fma_f32 v7, -v3, v6, v5
	v_fmac_f32_e32 v6, v7, v4
	v_fma_f32 v3, -v3, v6, v5
	v_div_fmas_f32 v3, v3, v4, v6
	v_div_fixup_f32 v18, v3, v2, 1.0
	global_load_dwordx4 v[2:5], v[14:15], off
	global_load_dwordx4 v[6:9], v[14:15], off offset:64
	s_waitcnt vmcnt(0)
	v_pk_mul_f32 v[12:13], v[18:19], v[12:13] op_sel_hi:[0,1]
	global_load_dwordx4 v[14:17], v[14:15], off offset:576
	v_pk_mul_f32 v[10:11], v[18:19], v[10:11] op_sel_hi:[0,1]
	v_pk_mul_f32 v[4:5], v[4:5], v[18:19] op_sel_hi:[1,0]
	v_pk_mul_f32 v[2:3], v[2:3], v[18:19] op_sel_hi:[1,0]
	v_pk_mul_f32 v[8:9], v[8:9], v[18:19] op_sel_hi:[1,0]
	v_pk_mul_f32 v[6:7], v[6:7], v[18:19] op_sel_hi:[1,0]
	s_waitcnt vmcnt(0)
	v_pk_mul_f32 v[16:17], v[18:19], v[16:17] op_sel_hi:[0,1]
	v_pk_mul_f32 v[14:15], v[18:19], v[14:15] op_sel_hi:[0,1]
	ds_read_b32 v19, v114 offset:1088
	v_add_u32_e32 v18, 0x4000, v0
	s_waitcnt lgkmcnt(0)
	v_div_scale_f32 v20, s[24:25], v19, v19, 1.0
	v_rcp_f32_e32 v21, v20
	s_nop 0
	v_fma_f32 v22, -v20, v21, 1.0
	v_fmac_f32_e32 v21, v22, v21
	v_div_scale_f32 v22, vcc, 1.0, v19, 1.0
	v_mul_f32_e32 v23, v22, v21
	v_fma_f32 v24, -v20, v23, v22
	v_fmac_f32_e32 v23, v24, v21
	v_fma_f32 v20, -v20, v23, v22
	v_div_fmas_f32 v20, v20, v21, v23
	v_div_fixup_f32 v34, v20, v19, 1.0
	v_mov_b32_e32 v19, v1
	v_lshl_add_u64 v[30:31], v[18:19], 2, s[20:21]
	global_load_dwordx4 v[18:21], v[30:31], off
	global_load_dwordx4 v[22:25], v[30:31], off offset:64
	global_load_dwordx4 v[26:29], v[30:31], off offset:512
	s_waitcnt vmcnt(2)
	v_pk_mul_f32 v[20:21], v[20:21], v[34:35] op_sel_hi:[1,0]
	global_load_dwordx4 v[30:33], v[30:31], off offset:576
	v_pk_mul_f32 v[18:19], v[18:19], v[34:35] op_sel_hi:[1,0]
	s_waitcnt vmcnt(2)
	v_pk_mul_f32 v[24:25], v[24:25], v[34:35] op_sel_hi:[1,0]
	v_pk_mul_f32 v[22:23], v[22:23], v[34:35] op_sel_hi:[1,0]
	s_waitcnt vmcnt(1)
	v_pk_mul_f32 v[28:29], v[34:35], v[28:29] op_sel_hi:[0,1]
	v_pk_mul_f32 v[26:27], v[34:35], v[26:27] op_sel_hi:[0,1]
	s_waitcnt vmcnt(0)
	v_pk_mul_f32 v[32:33], v[34:35], v[32:33] op_sel_hi:[0,1]
	v_pk_mul_f32 v[30:31], v[34:35], v[30:31] op_sel_hi:[0,1]
	ds_read_b32 v35, v114 offset:1152
	v_add_u32_e32 v34, 0x8000, v0
	s_waitcnt lgkmcnt(0)
	v_div_scale_f32 v36, s[24:25], v35, v35, 1.0
	v_rcp_f32_e32 v37, v36
	s_nop 0
	v_fma_f32 v38, -v36, v37, 1.0
	v_fmac_f32_e32 v37, v38, v37
	v_div_scale_f32 v38, vcc, 1.0, v35, 1.0
	v_mul_f32_e32 v39, v38, v37
	v_fma_f32 v40, -v36, v39, v38
	v_fmac_f32_e32 v39, v40, v37
	v_fma_f32 v36, -v36, v39, v38
	v_div_fmas_f32 v36, v36, v37, v39
	v_div_fixup_f32 v50, v36, v35, 1.0
	v_mov_b32_e32 v35, v1
	v_lshl_add_u64 v[46:47], v[34:35], 2, s[20:21]
	global_load_dwordx4 v[34:37], v[46:47], off
	global_load_dwordx4 v[38:41], v[46:47], off offset:64
	global_load_dwordx4 v[42:45], v[46:47], off offset:512
	s_waitcnt vmcnt(2)
	v_pk_mul_f32 v[36:37], v[36:37], v[50:51] op_sel_hi:[1,0]
	global_load_dwordx4 v[46:49], v[46:47], off offset:576
	v_pk_mul_f32 v[34:35], v[34:35], v[50:51] op_sel_hi:[1,0]
	s_waitcnt vmcnt(2)
	v_pk_mul_f32 v[40:41], v[40:41], v[50:51] op_sel_hi:[1,0]
	v_pk_mul_f32 v[38:39], v[38:39], v[50:51] op_sel_hi:[1,0]
	s_waitcnt vmcnt(1)
	v_pk_mul_f32 v[44:45], v[50:51], v[44:45] op_sel_hi:[0,1]
	v_pk_mul_f32 v[42:43], v[50:51], v[42:43] op_sel_hi:[0,1]
	s_waitcnt vmcnt(0)
	v_pk_mul_f32 v[48:49], v[50:51], v[48:49] op_sel_hi:[0,1]
	v_pk_mul_f32 v[46:47], v[50:51], v[46:47] op_sel_hi:[0,1]
	ds_read_b32 v51, v114 offset:1216
	v_add_u32_e32 v50, 0xc000, v0
	s_waitcnt lgkmcnt(0)
	v_div_scale_f32 v52, s[24:25], v51, v51, 1.0
	v_rcp_f32_e32 v53, v52
	s_nop 0
	v_fma_f32 v54, -v52, v53, 1.0
	v_fmac_f32_e32 v53, v54, v53
	v_div_scale_f32 v54, vcc, 1.0, v51, 1.0
	v_mul_f32_e32 v55, v54, v53
	v_fma_f32 v56, -v52, v55, v54
	v_fmac_f32_e32 v55, v56, v53
	v_fma_f32 v52, -v52, v55, v54
	v_div_fmas_f32 v52, v52, v53, v55
	v_div_fixup_f32 v66, v52, v51, 1.0
	v_mov_b32_e32 v51, v1
	v_lshl_add_u64 v[62:63], v[50:51], 2, s[20:21]
	global_load_dwordx4 v[50:53], v[62:63], off
	global_load_dwordx4 v[54:57], v[62:63], off offset:64
	global_load_dwordx4 v[58:61], v[62:63], off offset:512
	s_waitcnt vmcnt(2)
	v_pk_mul_f32 v[52:53], v[52:53], v[66:67] op_sel_hi:[1,0]
	global_load_dwordx4 v[62:65], v[62:63], off offset:576
	v_pk_mul_f32 v[50:51], v[50:51], v[66:67] op_sel_hi:[1,0]
	s_waitcnt vmcnt(2)
	v_pk_mul_f32 v[56:57], v[56:57], v[66:67] op_sel_hi:[1,0]
	v_pk_mul_f32 v[54:55], v[54:55], v[66:67] op_sel_hi:[1,0]
	s_waitcnt vmcnt(1)
; template <int EPI>
; __device__ __forceinline__ void gemm_acc_init(KP P, f32x4 (&acc)[2][2][4][2], int brow, int bcol, int wr, int wc, int fr_, int fq_, const float* sRu) {
;   if (EPI == EPI_OUTPROJ || EPI == EPI_RES) {
;     int fr = fr_, fq = fq_;
;     asm volatile("" : "+v"(fr), "+v"(fq));
;     const float* xin = (brow < MP ? P->in[0] + (size_t)brow * D : P->in[1] + (size_t)(brow - MP) * D) + bcol;
;     const bfu* xrb = (const bfu*)(P->ws + WS_XR) + (size_t)brow * D + bcol;
; #pragma unroll
;     for (int ai = 0; ai < 2; ++ai)
; #pragma unroll
;       for (int m = 0; m < 4; ++m) {
;         __builtin_amdgcn_sched_barrier(0);
;         unsigned lr = ai * 128 + wr * 64 + m * 16 + fr;
;         unsigned o = lr * D + wc * 32 + fq * 4;
;         float sc = 1.f;
;         if (EPI == EPI_OUTPROJ) sc = 1.f / sRu[lr];
; #pragma unroll
;         for (int bj = 0; bj < 2; ++bj)
; #pragma unroll
;           for (int n = 0; n < 2; ++n) {
;             if (EPI == EPI_RES) acc[ai][bj][m][n] = bf4_to_f32(*(const uint2*)(xrb + o + bj * 128 + n * 16));
;             else acc[ai][bj][m][n] = *(const f32x4*)(xin + o + bj * 128 + n * 16) * sc;
;           }
;       }
	v_pk_mul_f32 v[60:61], v[66:67], v[60:61] op_sel_hi:[0,1]
	v_pk_mul_f32 v[58:59], v[66:67], v[58:59] op_sel_hi:[0,1]
	s_waitcnt vmcnt(0)
	v_pk_mul_f32 v[64:65], v[66:67], v[64:65] op_sel_hi:[0,1]
	v_pk_mul_f32 v[62:63], v[66:67], v[62:63] op_sel_hi:[0,1]
	ds_read_b32 v67, v114 offset:1536
	v_add_u32_e32 v66, 0x20000, v0
	s_waitcnt lgkmcnt(0)
	v_div_scale_f32 v68, s[24:25], v67, v67, 1.0
	v_rcp_f32_e32 v69, v68
	s_nop 0
	v_fma_f32 v70, -v68, v69, 1.0
	v_fmac_f32_e32 v69, v70, v69
	v_div_scale_f32 v70, vcc, 1.0, v67, 1.0
	v_mul_f32_e32 v71, v70, v69
	v_fma_f32 v72, -v68, v71, v70
	v_fmac_f32_e32 v71, v72, v69
	v_fma_f32 v68, -v68, v71, v70
	v_div_fmas_f32 v68, v68, v69, v71
	v_div_fixup_f32 v82, v68, v67, 1.0
	v_mov_b32_e32 v67, v1
	v_lshl_add_u64 v[78:79], v[66:67], 2, s[20:21]
	global_load_dwordx4 v[66:69], v[78:79], off
	global_load_dwordx4 v[70:73], v[78:79], off offset:64
	global_load_dwordx4 v[74:77], v[78:79], off offset:512
	s_waitcnt vmcnt(2)
	v_pk_mul_f32 v[68:69], v[68:69], v[82:83] op_sel_hi:[1,0]
	global_load_dwordx4 v[78:81], v[78:79], off offset:576
	v_pk_mul_f32 v[66:67], v[66:67], v[82:83] op_sel_hi:[1,0]
	s_waitcnt vmcnt(2)
	v_pk_mul_f32 v[72:73], v[72:73], v[82:83] op_sel_hi:[1,0]
	v_pk_mul_f32 v[70:71], v[70:71], v[82:83] op_sel_hi:[1,0]
	s_waitcnt vmcnt(1)
	v_pk_mul_f32 v[76:77], v[82:83], v[76:77] op_sel_hi:[0,1]
	v_pk_mul_f32 v[74:75], v[82:83], v[74:75] op_sel_hi:[0,1]
	s_waitcnt vmcnt(0)
	v_pk_mul_f32 v[80:81], v[82:83], v[80:81] op_sel_hi:[0,1]
	v_pk_mul_f32 v[78:79], v[82:83], v[78:79] op_sel_hi:[0,1]
	ds_read_b32 v83, v114 offset:1600
	v_add_u32_e32 v82, 0x24000, v0
	s_waitcnt lgkmcnt(0)
	v_div_scale_f32 v84, s[24:25], v83, v83, 1.0
	v_rcp_f32_e32 v85, v84
	s_nop 0
	v_fma_f32 v86, -v84, v85, 1.0
	v_fmac_f32_e32 v85, v86, v85
	v_div_scale_f32 v86, vcc, 1.0, v83, 1.0
	v_mul_f32_e32 v87, v86, v85
	v_fma_f32 v88, -v84, v87, v86
	v_fmac_f32_e32 v87, v88, v85
	v_fma_f32 v84, -v84, v87, v86
	v_div_fmas_f32 v84, v84, v85, v87
	v_div_fixup_f32 v98, v84, v83, 1.0
	v_mov_b32_e32 v83, v1
	v_lshl_add_u64 v[94:95], v[82:83], 2, s[20:21]
	global_load_dwordx4 v[82:85], v[94:95], off
	global_load_dwordx4 v[86:89], v[94:95], off offset:64
	global_load_dwordx4 v[90:93], v[94:95], off offset:512
	s_waitcnt vmcnt(2)
	v_pk_mul_f32 v[84:85], v[84:85], v[98:99] op_sel_hi:[1,0]
	global_load_dwordx4 v[94:97], v[94:95], off offset:576
	v_pk_mul_f32 v[82:83], v[82:83], v[98:99] op_sel_hi:[1,0]
	s_waitcnt vmcnt(2)
	v_pk_mul_f32 v[88:89], v[88:89], v[98:99] op_sel_hi:[1,0]
	v_pk_mul_f32 v[86:87], v[86:87], v[98:99] op_sel_hi:[1,0]
	s_waitcnt vmcnt(1)
	v_pk_mul_f32 v[92:93], v[98:99], v[92:93] op_sel_hi:[0,1]
	v_pk_mul_f32 v[90:91], v[98:99], v[90:91] op_sel_hi:[0,1]
	s_waitcnt vmcnt(0)
	v_pk_mul_f32 v[96:97], v[98:99], v[96:97] op_sel_hi:[0,1]
	v_pk_mul_f32 v[94:95], v[98:99], v[94:95] op_sel_hi:[0,1]
	ds_read_b32 v99, v114 offset:1664
	v_add_u32_e32 v98, 0x28000, v0
	s_waitcnt lgkmcnt(0)
	v_div_scale_f32 v100, s[24:25], v99, v99, 1.0
	v_rcp_f32_e32 v101, v100
	s_nop 0
	v_fma_f32 v102, -v100, v101, 1.0
	v_fmac_f32_e32 v101, v102, v101
	v_div_scale_f32 v102, vcc, 1.0, v99, 1.0
	v_mul_f32_e32 v103, v102, v101
	v_fma_f32 v104, -v100, v103, v102
	v_fmac_f32_e32 v103, v104, v101
	v_fma_f32 v100, -v100, v103, v102
	v_div_fmas_f32 v100, v100, v101, v103
	v_div_fixup_f32 v116, v100, v99, 1.0
	v_mov_b32_e32 v99, v1
	v_lshl_add_u64 v[110:111], v[98:99], 2, s[20:21]
	global_load_dwordx4 v[98:101], v[110:111], off
	global_load_dwordx4 v[102:105], v[110:111], off offset:64
	global_load_dwordx4 v[106:109], v[110:111], off offset:512
	s_waitcnt vmcnt(2)
	v_pk_mul_f32 v[100:101], v[100:101], v[116:117] op_sel_hi:[1,0]
	global_load_dwordx4 v[110:113], v[110:111], off offset:576
	v_pk_mul_f32 v[98:99], v[98:99], v[116:117] op_sel_hi:[1,0]
	s_waitcnt vmcnt(2)
	v_pk_mul_f32 v[104:105], v[104:105], v[116:117] op_sel_hi:[1,0]
	v_pk_mul_f32 v[102:103], v[102:103], v[116:117] op_sel_hi:[1,0]
	s_waitcnt vmcnt(1)
	v_pk_mul_f32 v[108:109], v[116:117], v[108:109] op_sel_hi:[0,1]
	v_pk_mul_f32 v[106:107], v[116:117], v[106:107] op_sel_hi:[0,1]
	s_waitcnt vmcnt(0)
	v_pk_mul_f32 v[112:113], v[116:117], v[112:113] op_sel_hi:[0,1]
	v_pk_mul_f32 v[110:111], v[116:117], v[110:111] op_sel_hi:[0,1]
	ds_read_b32 v114, v114 offset:1728
	v_add_u32_e32 v0, 0x2c000, v0
	v_lshl_add_u64 v[126:127], v[0:1], 2, s[20:21]
	global_load_dwordx4 v[122:125], v[126:127], off offset:512
	s_mov_b64 s[20:21], 0
	s_waitcnt lgkmcnt(0)
	v_div_scale_f32 v115, s[24:25], v114, v114, 1.0
	v_rcp_f32_e32 v116, v115
	s_mov_b32 s74, s5
	v_fma_f32 v117, -v115, v116, 1.0
	v_fmac_f32_e32 v116, v117, v116
	v_div_scale_f32 v117, vcc, 1.0, v114, 1.0
	v_mul_f32_e32 v118, v117, v116
	v_fma_f32 v119, -v115, v118, v117
	v_fmac_f32_e32 v118, v119, v116
	v_fma_f32 v115, -v115, v118, v117
	v_div_fmas_f32 v115, v115, v116, v118
	v_div_fixup_f32 v138, v115, v114, 1.0
	global_load_dwordx4 v[114:117], v[126:127], off
	global_load_dwordx4 v[118:121], v[126:127], off offset:64
	s_waitcnt vmcnt(2)
	v_pk_mul_f32 v[124:125], v[138:139], v[124:125] op_sel_hi:[0,1]
	global_load_dwordx4 v[126:129], v[126:127], off offset:576
	v_pk_mul_f32 v[122:123], v[138:139], v[122:123] op_sel_hi:[0,1]
	s_waitcnt vmcnt(2)
	v_pk_mul_f32 v[116:117], v[116:117], v[138:139] op_sel_hi:[1,0]
	v_pk_mul_f32 v[114:115], v[114:115], v[138:139] op_sel_hi:[1,0]
	s_waitcnt vmcnt(1)
	v_pk_mul_f32 v[120:121], v[120:121], v[138:139] op_sel_hi:[1,0]
	v_pk_mul_f32 v[118:119], v[118:119], v[138:139] op_sel_hi:[1,0]
	s_waitcnt vmcnt(0)
	v_pk_mul_f32 v[128:129], v[138:139], v[128:129] op_sel_hi:[0,1]
	v_pk_mul_f32 v[126:127], v[138:139], v[126:127] op_sel_hi:[0,1]
	s_branch .LBB0_306

; __device__ __forceinline__ float silu_f(float x) { return x * __builtin_amdgcn_rcpf(1.f + __expf(-x)); }
; __device__ __forceinline__ void phase_ssd(KP P, char* smem, const int wv) {
;     ...
;       if (conv_role) {
;         const float* wcol = sWc + cgp * 8;
;         u32x4 ovr[8];
; #pragma unroll
;         for (int e2 = 0; e2 < 4; ++e2) {
;           __builtin_amdgcn_sched_barrier(0);
;           float w0[4], w1[4];
; #pragma unroll
;           for (int tap = 0; tap < 4; ++tap) { w0[tap] = wcol[tap * 384 + 2 * e2]; w1[tap] = wcol[tap * 384 + 2 * e2 + 1]; }
;           const float bl = wcol[4 * 384 + 2 * e2], bh = wcol[4 * 384 + 2 * e2 + 1];
; #pragma unroll
;           for (int i = 0; i < 8; ++i) {
;             float ylo = bl, yhi = bh;
; #pragma unroll
;             for (int tap = 0; tap < 4; ++tap) {
;               unsigned rw = pre[i + tap][e2];
;               ylo += w0[tap] * __uint_as_float(rw << 16);
;               yhi += w1[tap] * __uint_as_float(rw & 0xffff0000u);
;             }
;             ovr[i][e2] = cvt_pk_bf16(silu_f(ylo), silu_f(yhi));
;           }
;         }
.LBB0_417:
	s_andn2_b64 vcc, exec, s[34:35]
	s_cbranch_vccnz .LBB0_423
	v_add_u32_e32 v0, 0x600, v114
	v_add_u32_e32 v151, 0xc00, v114
	v_add_u32_e32 v153, 0x1200, v114
	v_add_u32_e32 v207, 0x1800, v114
	v_mov_b32_e32 v234, 0xbfb8aa3b
	v_mov_b32_e32 v235, 0xbfb8aa3b
	ds_read2_b32 v[156:157], v114 offset1:1
	ds_read2_b32 v[158:159], v0 offset1:1
	ds_read2_b32 v[160:161], v151 offset1:1
	ds_read2_b32 v[162:163], v153 offset1:1
	ds_read2_b32 v[154:155], v207 offset1:1
	s_waitcnt vmcnt(1)
	v_lshlrev_b32_e32 v212, 16, v36
	v_and_b32_e32 v213, 0xffff0000, v36
	v_lshlrev_b32_e32 v214, 16, v40
	v_and_b32_e32 v215, 0xffff0000, v40
	v_lshlrev_b32_e32 v216, 16, v44
	v_and_b32_e32 v217, 0xffff0000, v44
	v_lshlrev_b32_e32 v218, 16, v48
	v_and_b32_e32 v219, 0xffff0000, v48
	v_lshlrev_b32_e32 v220, 16, v52
	v_and_b32_e32 v221, 0xffff0000, v52
	v_lshlrev_b32_e32 v222, 16, v56
	v_and_b32_e32 v223, 0xffff0000, v56
	v_lshlrev_b32_e32 v224, 16, v60
	v_and_b32_e32 v225, 0xffff0000, v60
	v_lshlrev_b32_e32 v226, 16, v64
	v_and_b32_e32 v227, 0xffff0000, v64
	v_lshlrev_b32_e32 v228, 16, v68
	v_and_b32_e32 v229, 0xffff0000, v68
	v_lshlrev_b32_e32 v230, 16, v72
	v_and_b32_e32 v231, 0xffff0000, v72
	v_lshlrev_b32_e32 v232, 16, v76
	v_and_b32_e32 v233, 0xffff0000, v76
	s_waitcnt lgkmcnt(0)
	v_pk_fma_f32 v[236:237], v[156:157], v[212:213], v[154:155]
	v_pk_fma_f32 v[208:209], v[156:157], v[214:215], v[154:155]
	v_pk_fma_f32 v[236:237], v[158:159], v[214:215], v[236:237]
	v_pk_fma_f32 v[208:209], v[158:159], v[216:217], v[208:209]
	v_pk_fma_f32 v[236:237], v[160:161], v[216:217], v[236:237]
	v_pk_fma_f32 v[208:209], v[160:161], v[218:219], v[208:209]
	v_pk_fma_f32 v[236:237], v[162:163], v[218:219], v[236:237]
	v_pk_fma_f32 v[208:209], v[162:163], v[220:221], v[208:209]
	v_pk_mul_f32 v[238:239], v[234:235], v[236:237]
	v_pk_mul_f32 v[210:211], v[234:235], v[208:209]
	v_exp_f32_e32 v238, v238
	v_exp_f32_e32 v210, v210
	v_exp_f32_e32 v239, v239
	v_exp_f32_e32 v211, v211
	v_pk_add_f32 v[238:239], v[238:239], 1.0 op_sel_hi:[1,0]
	v_pk_add_f32 v[210:211], v[210:211], 1.0 op_sel_hi:[1,0]
	v_rcp_f32_e32 v238, v238
	v_rcp_f32_e32 v210, v210
	v_rcp_f32_e32 v239, v239
	v_rcp_f32_e32 v211, v211
	v_pk_mul_f32 v[236:237], v[236:237], v[238:239]
	v_pk_mul_f32 v[208:209], v[208:209], v[210:211]
	v_cvt_pk_bf16_f32 v80, v236, v237
	v_cvt_pk_bf16_f32 v84, v208, v209
	v_pk_fma_f32 v[236:237], v[156:157], v[216:217], v[154:155]
	v_pk_fma_f32 v[208:209], v[156:157], v[218:219], v[154:155]
	v_pk_fma_f32 v[236:237], v[158:159], v[218:219], v[236:237]
	v_pk_fma_f32 v[208:209], v[158:159], v[220:221], v[208:209]
	v_pk_fma_f32 v[236:237], v[160:161], v[220:221], v[236:237]
	v_pk_fma_f32 v[208:209], v[160:161], v[222:223], v[208:209]
	v_pk_fma_f32 v[236:237], v[162:163], v[222:223], v[236:237]
	v_pk_fma_f32 v[208:209], v[162:163], v[224:225], v[208:209]
	v_pk_mul_f32 v[238:239], v[234:235], v[236:237]
	v_pk_mul_f32 v[210:211], v[234:235], v[208:209]
	v_exp_f32_e32 v238, v238
	v_exp_f32_e32 v210, v210
	v_exp_f32_e32 v239, v239
	v_exp_f32_e32 v211, v211
	v_pk_add_f32 v[238:239], v[238:239], 1.0 op_sel_hi:[1,0]
	v_pk_add_f32 v[210:211], v[210:211], 1.0 op_sel_hi:[1,0]
	v_rcp_f32_e32 v238, v238
	v_rcp_f32_e32 v210, v210
	v_rcp_f32_e32 v239, v239
	v_rcp_f32_e32 v211, v211
	v_pk_mul_f32 v[236:237], v[236:237], v[238:239]
	v_pk_mul_f32 v[208:209], v[208:209], v[210:211]
	v_cvt_pk_bf16_f32 v88, v236, v237
	v_cvt_pk_bf16_f32 v92, v208, v209
	v_pk_fma_f32 v[236:237], v[156:157], v[220:221], v[154:155]
	v_pk_fma_f32 v[208:209], v[156:157], v[222:223], v[154:155]
	v_pk_fma_f32 v[236:237], v[158:159], v[222:223], v[236:237]
	v_pk_fma_f32 v[208:209], v[158:159], v[224:225], v[208:209]
	v_pk_fma_f32 v[236:237], v[160:161], v[224:225], v[236:237]
	v_pk_fma_f32 v[208:209], v[160:161], v[226:227], v[208:209]
	v_pk_fma_f32 v[236:237], v[162:163], v[226:227], v[236:237]
	v_pk_fma_f32 v[208:209], v[162:163], v[228:229], v[208:209]
	v_pk_mul_f32 v[238:239], v[234:235], v[236:237]
	v_pk_mul_f32 v[210:211], v[234:235], v[208:209]
	v_exp_f32_e32 v238, v238
	v_exp_f32_e32 v210, v210
	v_exp_f32_e32 v239, v239
	v_exp_f32_e32 v211, v211
	v_pk_add_f32 v[238:239], v[238:239], 1.0 op_sel_hi:[1,0]
	v_pk_add_f32 v[210:211], v[210:211], 1.0 op_sel_hi:[1,0]
	v_rcp_f32_e32 v238, v238
	v_rcp_f32_e32 v210, v210
	v_rcp_f32_e32 v239, v239
	v_rcp_f32_e32 v211, v211
	v_pk_mul_f32 v[236:237], v[236:237], v[238:239]
	v_pk_mul_f32 v[208:209], v[208:209], v[210:211]
	v_cvt_pk_bf16_f32 v96, v236, v237
	v_cvt_pk_bf16_f32 v100, v208, v209
	v_pk_fma_f32 v[236:237], v[156:157], v[224:225], v[154:155]
	v_pk_fma_f32 v[208:209], v[156:157], v[226:227], v[154:155]
	v_pk_fma_f32 v[236:237], v[158:159], v[226:227], v[236:237]
	v_pk_fma_f32 v[208:209], v[158:159], v[228:229], v[208:209]
	v_pk_fma_f32 v[236:237], v[160:161], v[228:229], v[236:237]
	v_pk_fma_f32 v[208:209], v[160:161], v[230:231], v[208:209]
	v_pk_fma_f32 v[236:237], v[162:163], v[230:231], v[236:237]
	v_pk_fma_f32 v[208:209], v[162:163], v[232:233], v[208:209]
	v_pk_mul_f32 v[238:239], v[234:235], v[236:237]
	v_pk_mul_f32 v[210:211], v[234:235], v[208:209]
	v_exp_f32_e32 v238, v238
	v_exp_f32_e32 v210, v210
	v_exp_f32_e32 v239, v239
	v_exp_f32_e32 v211, v211
	v_pk_add_f32 v[238:239], v[238:239], 1.0 op_sel_hi:[1,0]
	v_pk_add_f32 v[210:211], v[210:211], 1.0 op_sel_hi:[1,0]
	v_rcp_f32_e32 v238, v238
	v_rcp_f32_e32 v210, v210
	v_rcp_f32_e32 v239, v239
	v_rcp_f32_e32 v211, v211
	v_pk_mul_f32 v[236:237], v[236:237], v[238:239]
	v_pk_mul_f32 v[208:209], v[208:209], v[210:211]
	v_cvt_pk_bf16_f32 v104, v236, v237
	v_cvt_pk_bf16_f32 v108, v208, v209
	ds_read2_b32 v[156:157], v114 offset0:2 offset1:3
	ds_read2_b32 v[158:159], v0 offset0:2 offset1:3
	ds_read2_b32 v[160:161], v151 offset0:2 offset1:3
	ds_read2_b32 v[162:163], v153 offset0:2 offset1:3
	ds_read2_b32 v[154:155], v207 offset0:2 offset1:3
	v_lshlrev_b32_e32 v212, 16, v37
	v_and_b32_e32 v213, 0xffff0000, v37
	v_lshlrev_b32_e32 v214, 16, v41
	v_and_b32_e32 v215, 0xffff0000, v41
	v_lshlrev_b32_e32 v216, 16, v45
	v_and_b32_e32 v217, 0xffff0000, v45
	v_lshlrev_b32_e32 v218, 16, v49
	v_and_b32_e32 v219, 0xffff0000, v49
	v_lshlrev_b32_e32 v220, 16, v53
	v_and_b32_e32 v221, 0xffff0000, v53
	v_lshlrev_b32_e32 v222, 16, v57
	v_and_b32_e32 v223, 0xffff0000, v57
	v_lshlrev_b32_e32 v224, 16, v61
	v_and_b32_e32 v225, 0xffff0000, v61
	v_lshlrev_b32_e32 v226, 16, v65
	v_and_b32_e32 v227, 0xffff0000, v65
	v_lshlrev_b32_e32 v228, 16, v69
	v_and_b32_e32 v229, 0xffff0000, v69
	v_lshlrev_b32_e32 v230, 16, v73
	v_and_b32_e32 v231, 0xffff0000, v73
	v_lshlrev_b32_e32 v232, 16, v77
	v_and_b32_e32 v233, 0xffff0000, v77
	s_waitcnt lgkmcnt(0)
; __device__ __forceinline__ float silu_f(float x) { return x * __builtin_amdgcn_rcpf(1.f + __expf(-x)); }
; __device__ __forceinline__ void phase_ssd(KP P, char* smem, const int wv) {
;     ...
;         for (int e2 = 0; e2 < 4; ++e2) {
;           __builtin_amdgcn_sched_barrier(0);
;           float w0[4], w1[4];
; #pragma unroll
;           for (int tap = 0; tap < 4; ++tap) { w0[tap] = wcol[tap * 384 + 2 * e2]; w1[tap] = wcol[tap * 384 + 2 * e2 + 1]; }
;           const float bl = wcol[4 * 384 + 2 * e2], bh = wcol[4 * 384 + 2 * e2 + 1];
; #pragma unroll
;           for (int i = 0; i < 8; ++i) {
;             float ylo = bl, yhi = bh;
; #pragma unroll
;             for (int tap = 0; tap < 4; ++tap) {
;               unsigned rw = pre[i + tap][e2];
;               ylo += w0[tap] * __uint_as_float(rw << 16);
;               yhi += w1[tap] * __uint_as_float(rw & 0xffff0000u);
;             }
;             ovr[i][e2] = cvt_pk_bf16(silu_f(ylo), silu_f(yhi));
;           }
;         }
	v_pk_fma_f32 v[236:237], v[156:157], v[212:213], v[154:155]
	v_pk_fma_f32 v[208:209], v[156:157], v[214:215], v[154:155]
	v_pk_fma_f32 v[236:237], v[158:159], v[214:215], v[236:237]
	v_pk_fma_f32 v[208:209], v[158:159], v[216:217], v[208:209]
	v_pk_fma_f32 v[236:237], v[160:161], v[216:217], v[236:237]
	v_pk_fma_f32 v[208:209], v[160:161], v[218:219], v[208:209]
	v_pk_fma_f32 v[236:237], v[162:163], v[218:219], v[236:237]
	v_pk_fma_f32 v[208:209], v[162:163], v[220:221], v[208:209]
	v_pk_mul_f32 v[238:239], v[234:235], v[236:237]
	v_pk_mul_f32 v[210:211], v[234:235], v[208:209]
	v_exp_f32_e32 v238, v238
	v_exp_f32_e32 v210, v210
	v_exp_f32_e32 v239, v239
	v_exp_f32_e32 v211, v211
	v_pk_add_f32 v[238:239], v[238:239], 1.0 op_sel_hi:[1,0]
	v_pk_add_f32 v[210:211], v[210:211], 1.0 op_sel_hi:[1,0]
	v_rcp_f32_e32 v238, v238
	v_rcp_f32_e32 v210, v210
	v_rcp_f32_e32 v239, v239
	v_rcp_f32_e32 v211, v211
	v_pk_mul_f32 v[236:237], v[236:237], v[238:239]
	v_pk_mul_f32 v[208:209], v[208:209], v[210:211]
	v_cvt_pk_bf16_f32 v81, v236, v237
	v_cvt_pk_bf16_f32 v85, v208, v209
	v_pk_fma_f32 v[236:237], v[156:157], v[216:217], v[154:155]
	v_pk_fma_f32 v[208:209], v[156:157], v[218:219], v[154:155]
	v_pk_fma_f32 v[236:237], v[158:159], v[218:219], v[236:237]
	v_pk_fma_f32 v[208:209], v[158:159], v[220:221], v[208:209]
	v_pk_fma_f32 v[236:237], v[160:161], v[220:221], v[236:237]
	v_pk_fma_f32 v[208:209], v[160:161], v[222:223], v[208:209]
	v_pk_fma_f32 v[236:237], v[162:163], v[222:223], v[236:237]
	v_pk_fma_f32 v[208:209], v[162:163], v[224:225], v[208:209]
	v_pk_mul_f32 v[238:239], v[234:235], v[236:237]
	v_pk_mul_f32 v[210:211], v[234:235], v[208:209]
	v_exp_f32_e32 v238, v238
	v_exp_f32_e32 v210, v210
	v_exp_f32_e32 v239, v239
	v_exp_f32_e32 v211, v211
	v_pk_add_f32 v[238:239], v[238:239], 1.0 op_sel_hi:[1,0]
	v_pk_add_f32 v[210:211], v[210:211], 1.0 op_sel_hi:[1,0]
	v_rcp_f32_e32 v238, v238
	v_rcp_f32_e32 v210, v210
	v_rcp_f32_e32 v239, v239
	v_rcp_f32_e32 v211, v211
	v_pk_mul_f32 v[236:237], v[236:237], v[238:239]
	v_pk_mul_f32 v[208:209], v[208:209], v[210:211]
	v_cvt_pk_bf16_f32 v89, v236, v237
	v_cvt_pk_bf16_f32 v93, v208, v209
	v_pk_fma_f32 v[236:237], v[156:157], v[220:221], v[154:155]
	v_pk_fma_f32 v[208:209], v[156:157], v[222:223], v[154:155]
	v_pk_fma_f32 v[236:237], v[158:159], v[222:223], v[236:237]
	v_pk_fma_f32 v[208:209], v[158:159], v[224:225], v[208:209]
	v_pk_fma_f32 v[236:237], v[160:161], v[224:225], v[236:237]
	v_pk_fma_f32 v[208:209], v[160:161], v[226:227], v[208:209]
	v_pk_fma_f32 v[236:237], v[162:163], v[226:227], v[236:237]
	v_pk_fma_f32 v[208:209], v[162:163], v[228:229], v[208:209]
	v_pk_mul_f32 v[238:239], v[234:235], v[236:237]
	v_pk_mul_f32 v[210:211], v[234:235], v[208:209]
	v_exp_f32_e32 v238, v238
	v_exp_f32_e32 v210, v210
	v_exp_f32_e32 v239, v239
	v_exp_f32_e32 v211, v211
	v_pk_add_f32 v[238:239], v[238:239], 1.0 op_sel_hi:[1,0]
	v_pk_add_f32 v[210:211], v[210:211], 1.0 op_sel_hi:[1,0]
	v_rcp_f32_e32 v238, v238
	v_rcp_f32_e32 v210, v210
	v_rcp_f32_e32 v239, v239
	v_rcp_f32_e32 v211, v211
	v_pk_mul_f32 v[236:237], v[236:237], v[238:239]
	v_pk_mul_f32 v[208:209], v[208:209], v[210:211]
	v_cvt_pk_bf16_f32 v97, v236, v237
	v_cvt_pk_bf16_f32 v101, v208, v209
	v_pk_fma_f32 v[236:237], v[156:157], v[224:225], v[154:155]
	v_pk_fma_f32 v[208:209], v[156:157], v[226:227], v[154:155]
	v_pk_fma_f32 v[236:237], v[158:159], v[226:227], v[236:237]
	v_pk_fma_f32 v[208:209], v[158:159], v[228:229], v[208:209]
	v_pk_fma_f32 v[236:237], v[160:161], v[228:229], v[236:237]
	v_pk_fma_f32 v[208:209], v[160:161], v[230:231], v[208:209]
	v_pk_fma_f32 v[236:237], v[162:163], v[230:231], v[236:237]
	v_pk_fma_f32 v[208:209], v[162:163], v[232:233], v[208:209]
	v_pk_mul_f32 v[238:239], v[234:235], v[236:237]
	v_pk_mul_f32 v[210:211], v[234:235], v[208:209]
	v_exp_f32_e32 v238, v238
	v_exp_f32_e32 v210, v210
	v_exp_f32_e32 v239, v239
	v_exp_f32_e32 v211, v211
	v_pk_add_f32 v[238:239], v[238:239], 1.0 op_sel_hi:[1,0]
	v_pk_add_f32 v[210:211], v[210:211], 1.0 op_sel_hi:[1,0]
	v_rcp_f32_e32 v238, v238
	v_rcp_f32_e32 v210, v210
	v_rcp_f32_e32 v239, v239
	v_rcp_f32_e32 v211, v211
	v_pk_mul_f32 v[236:237], v[236:237], v[238:239]
	v_pk_mul_f32 v[208:209], v[208:209], v[210:211]
	v_cvt_pk_bf16_f32 v105, v236, v237
	v_cvt_pk_bf16_f32 v109, v208, v209
	ds_read2_b32 v[156:157], v114 offset0:4 offset1:5
	ds_read2_b32 v[158:159], v0 offset0:4 offset1:5
	ds_read2_b32 v[160:161], v151 offset0:4 offset1:5
	ds_read2_b32 v[162:163], v153 offset0:4 offset1:5
	ds_read2_b32 v[154:155], v207 offset0:4 offset1:5
	v_lshlrev_b32_e32 v212, 16, v38
	v_and_b32_e32 v213, 0xffff0000, v38
	v_lshlrev_b32_e32 v214, 16, v42
	v_and_b32_e32 v215, 0xffff0000, v42
	v_lshlrev_b32_e32 v216, 16, v46
	v_and_b32_e32 v217, 0xffff0000, v46
	v_lshlrev_b32_e32 v218, 16, v50
	v_and_b32_e32 v219, 0xffff0000, v50
	v_lshlrev_b32_e32 v220, 16, v54
	v_and_b32_e32 v221, 0xffff0000, v54
	v_lshlrev_b32_e32 v222, 16, v58
	v_and_b32_e32 v223, 0xffff0000, v58
	v_lshlrev_b32_e32 v224, 16, v62
	v_and_b32_e32 v225, 0xffff0000, v62
	v_lshlrev_b32_e32 v226, 16, v66
	v_and_b32_e32 v227, 0xffff0000, v66
	v_lshlrev_b32_e32 v228, 16, v70
	v_and_b32_e32 v229, 0xffff0000, v70
	v_lshlrev_b32_e32 v230, 16, v74
	v_and_b32_e32 v231, 0xffff0000, v74
	v_lshlrev_b32_e32 v232, 16, v78
	v_and_b32_e32 v233, 0xffff0000, v78
	s_waitcnt lgkmcnt(0)
; __device__ __forceinline__ float silu_f(float x) { return x * __builtin_amdgcn_rcpf(1.f + __expf(-x)); }
; __device__ __forceinline__ void phase_ssd(KP P, char* smem, const int wv) {
;     ...
;         for (int e2 = 0; e2 < 4; ++e2) {
;           __builtin_amdgcn_sched_barrier(0);
;           float w0[4], w1[4];
; #pragma unroll
;           for (int tap = 0; tap < 4; ++tap) { w0[tap] = wcol[tap * 384 + 2 * e2]; w1[tap] = wcol[tap * 384 + 2 * e2 + 1]; }
;           const float bl = wcol[4 * 384 + 2 * e2], bh = wcol[4 * 384 + 2 * e2 + 1];
; #pragma unroll
;           for (int i = 0; i < 8; ++i) {
;             float ylo = bl, yhi = bh;
; #pragma unroll
;             for (int tap = 0; tap < 4; ++tap) {
;               unsigned rw = pre[i + tap][e2];
;               ylo += w0[tap] * __uint_as_float(rw << 16);
;               yhi += w1[tap] * __uint_as_float(rw & 0xffff0000u);
;             }
;             ovr[i][e2] = cvt_pk_bf16(silu_f(ylo), silu_f(yhi));
;           }
;         }
	v_pk_fma_f32 v[236:237], v[156:157], v[212:213], v[154:155]
	v_pk_fma_f32 v[208:209], v[156:157], v[214:215], v[154:155]
	v_pk_fma_f32 v[236:237], v[158:159], v[214:215], v[236:237]
	v_pk_fma_f32 v[208:209], v[158:159], v[216:217], v[208:209]
	v_pk_fma_f32 v[236:237], v[160:161], v[216:217], v[236:237]
	v_pk_fma_f32 v[208:209], v[160:161], v[218:219], v[208:209]
	v_pk_fma_f32 v[236:237], v[162:163], v[218:219], v[236:237]
	v_pk_fma_f32 v[208:209], v[162:163], v[220:221], v[208:209]
	v_pk_mul_f32 v[238:239], v[234:235], v[236:237]
	v_pk_mul_f32 v[210:211], v[234:235], v[208:209]
	v_exp_f32_e32 v238, v238
	v_exp_f32_e32 v210, v210
	v_exp_f32_e32 v239, v239
	v_exp_f32_e32 v211, v211
	v_pk_add_f32 v[238:239], v[238:239], 1.0 op_sel_hi:[1,0]
	v_pk_add_f32 v[210:211], v[210:211], 1.0 op_sel_hi:[1,0]
	v_rcp_f32_e32 v238, v238
	v_rcp_f32_e32 v210, v210
	v_rcp_f32_e32 v239, v239
	v_rcp_f32_e32 v211, v211
	v_pk_mul_f32 v[236:237], v[236:237], v[238:239]
	v_pk_mul_f32 v[208:209], v[208:209], v[210:211]
	v_cvt_pk_bf16_f32 v82, v236, v237
	v_cvt_pk_bf16_f32 v86, v208, v209
	v_pk_fma_f32 v[236:237], v[156:157], v[216:217], v[154:155]
	v_pk_fma_f32 v[208:209], v[156:157], v[218:219], v[154:155]
	v_pk_fma_f32 v[236:237], v[158:159], v[218:219], v[236:237]
	v_pk_fma_f32 v[208:209], v[158:159], v[220:221], v[208:209]
	v_pk_fma_f32 v[236:237], v[160:161], v[220:221], v[236:237]
	v_pk_fma_f32 v[208:209], v[160:161], v[222:223], v[208:209]
	v_pk_fma_f32 v[236:237], v[162:163], v[222:223], v[236:237]
	v_pk_fma_f32 v[208:209], v[162:163], v[224:225], v[208:209]
	v_pk_mul_f32 v[238:239], v[234:235], v[236:237]
	v_pk_mul_f32 v[210:211], v[234:235], v[208:209]
	v_exp_f32_e32 v238, v238
	v_exp_f32_e32 v210, v210
	v_exp_f32_e32 v239, v239
	v_exp_f32_e32 v211, v211
	v_pk_add_f32 v[238:239], v[238:239], 1.0 op_sel_hi:[1,0]
	v_pk_add_f32 v[210:211], v[210:211], 1.0 op_sel_hi:[1,0]
	v_rcp_f32_e32 v238, v238
	v_rcp_f32_e32 v210, v210
	v_rcp_f32_e32 v239, v239
	v_rcp_f32_e32 v211, v211
	v_pk_mul_f32 v[236:237], v[236:237], v[238:239]
	v_pk_mul_f32 v[208:209], v[208:209], v[210:211]
	v_cvt_pk_bf16_f32 v90, v236, v237
	v_cvt_pk_bf16_f32 v94, v208, v209
	v_pk_fma_f32 v[236:237], v[156:157], v[220:221], v[154:155]
	v_pk_fma_f32 v[208:209], v[156:157], v[222:223], v[154:155]
	v_pk_fma_f32 v[236:237], v[158:159], v[222:223], v[236:237]
	v_pk_fma_f32 v[208:209], v[158:159], v[224:225], v[208:209]
	v_pk_fma_f32 v[236:237], v[160:161], v[224:225], v[236:237]
	v_pk_fma_f32 v[208:209], v[160:161], v[226:227], v[208:209]
	v_pk_fma_f32 v[236:237], v[162:163], v[226:227], v[236:237]
	v_pk_fma_f32 v[208:209], v[162:163], v[228:229], v[208:209]
	v_pk_mul_f32 v[238:239], v[234:235], v[236:237]
	v_pk_mul_f32 v[210:211], v[234:235], v[208:209]
	v_exp_f32_e32 v238, v238
	v_exp_f32_e32 v210, v210
	v_exp_f32_e32 v239, v239
	v_exp_f32_e32 v211, v211
	v_pk_add_f32 v[238:239], v[238:239], 1.0 op_sel_hi:[1,0]
	v_pk_add_f32 v[210:211], v[210:211], 1.0 op_sel_hi:[1,0]
	v_rcp_f32_e32 v238, v238
	v_rcp_f32_e32 v210, v210
	v_rcp_f32_e32 v239, v239
	v_rcp_f32_e32 v211, v211
	v_pk_mul_f32 v[236:237], v[236:237], v[238:239]
	v_pk_mul_f32 v[208:209], v[208:209], v[210:211]
	v_cvt_pk_bf16_f32 v98, v236, v237
	v_cvt_pk_bf16_f32 v102, v208, v209
	v_pk_fma_f32 v[236:237], v[156:157], v[224:225], v[154:155]
	v_pk_fma_f32 v[208:209], v[156:157], v[226:227], v[154:155]
	v_pk_fma_f32 v[236:237], v[158:159], v[226:227], v[236:237]
	v_pk_fma_f32 v[208:209], v[158:159], v[228:229], v[208:209]
	v_pk_fma_f32 v[236:237], v[160:161], v[228:229], v[236:237]
	v_pk_fma_f32 v[208:209], v[160:161], v[230:231], v[208:209]
	v_pk_fma_f32 v[236:237], v[162:163], v[230:231], v[236:237]
	v_pk_fma_f32 v[208:209], v[162:163], v[232:233], v[208:209]
	v_pk_mul_f32 v[238:239], v[234:235], v[236:237]
	v_pk_mul_f32 v[210:211], v[234:235], v[208:209]
	v_exp_f32_e32 v238, v238
	v_exp_f32_e32 v210, v210
	v_exp_f32_e32 v239, v239
	v_exp_f32_e32 v211, v211
	v_pk_add_f32 v[238:239], v[238:239], 1.0 op_sel_hi:[1,0]
	v_pk_add_f32 v[210:211], v[210:211], 1.0 op_sel_hi:[1,0]
	v_rcp_f32_e32 v238, v238
	v_rcp_f32_e32 v210, v210
	v_rcp_f32_e32 v239, v239
	v_rcp_f32_e32 v211, v211
	v_pk_mul_f32 v[236:237], v[236:237], v[238:239]
	v_pk_mul_f32 v[208:209], v[208:209], v[210:211]
	v_cvt_pk_bf16_f32 v106, v236, v237
	v_cvt_pk_bf16_f32 v110, v208, v209
	ds_read2_b32 v[156:157], v114 offset0:6 offset1:7
	ds_read2_b32 v[158:159], v0 offset0:6 offset1:7
	ds_read2_b32 v[160:161], v151 offset0:6 offset1:7
	ds_read2_b32 v[162:163], v153 offset0:6 offset1:7
	ds_read2_b32 v[154:155], v207 offset0:6 offset1:7
	v_lshlrev_b32_e32 v212, 16, v39
	v_and_b32_e32 v213, 0xffff0000, v39
	v_lshlrev_b32_e32 v214, 16, v43
	v_and_b32_e32 v215, 0xffff0000, v43
	v_lshlrev_b32_e32 v216, 16, v47
	v_and_b32_e32 v217, 0xffff0000, v47
	v_lshlrev_b32_e32 v218, 16, v51
	v_and_b32_e32 v219, 0xffff0000, v51
	v_lshlrev_b32_e32 v220, 16, v55
	v_and_b32_e32 v221, 0xffff0000, v55
	v_lshlrev_b32_e32 v222, 16, v59
	v_and_b32_e32 v223, 0xffff0000, v59
	v_lshlrev_b32_e32 v224, 16, v63
	v_and_b32_e32 v225, 0xffff0000, v63
	v_lshlrev_b32_e32 v226, 16, v67
	v_and_b32_e32 v227, 0xffff0000, v67
	v_lshlrev_b32_e32 v228, 16, v71
	v_and_b32_e32 v229, 0xffff0000, v71
	v_lshlrev_b32_e32 v230, 16, v75
	v_and_b32_e32 v231, 0xffff0000, v75
	v_lshlrev_b32_e32 v232, 16, v79
	v_and_b32_e32 v233, 0xffff0000, v79
	s_waitcnt lgkmcnt(0)
; __device__ __forceinline__ float silu_f(float x) { return x * __builtin_amdgcn_rcpf(1.f + __expf(-x)); }
; __device__ __forceinline__ void phase_ssd(KP P, char* smem, const int wv) {
;     ...
;         for (int e2 = 0; e2 < 4; ++e2) {
;           __builtin_amdgcn_sched_barrier(0);
;           float w0[4], w1[4];
; #pragma unroll
;           for (int tap = 0; tap < 4; ++tap) { w0[tap] = wcol[tap * 384 + 2 * e2]; w1[tap] = wcol[tap * 384 + 2 * e2 + 1]; }
;           const float bl = wcol[4 * 384 + 2 * e2], bh = wcol[4 * 384 + 2 * e2 + 1];
; #pragma unroll
;           for (int i = 0; i < 8; ++i) {
;             float ylo = bl, yhi = bh;
; #pragma unroll
;             for (int tap = 0; tap < 4; ++tap) {
;               unsigned rw = pre[i + tap][e2];
;               ylo += w0[tap] * __uint_as_float(rw << 16);
;               yhi += w1[tap] * __uint_as_float(rw & 0xffff0000u);
;             }
;             ovr[i][e2] = cvt_pk_bf16(silu_f(ylo), silu_f(yhi));
;           }
;         }
;         if (cgp >= 16) {
;           bfu* rowdst = (cgp < 32) ? (sB + (cgp - 16) * 8) : (sC + (cgp - 32) * 8);
; #pragma unroll
;           for (int i = 0; i < 8; ++i) *(u32x4*)(rowdst + (rs * 8 + i) * S_LDB) = ovr[i];
;         }
	v_pk_fma_f32 v[236:237], v[156:157], v[212:213], v[154:155]
	v_pk_fma_f32 v[208:209], v[156:157], v[214:215], v[154:155]
	v_pk_fma_f32 v[236:237], v[158:159], v[214:215], v[236:237]
	v_pk_fma_f32 v[208:209], v[158:159], v[216:217], v[208:209]
	v_pk_fma_f32 v[236:237], v[160:161], v[216:217], v[236:237]
	v_pk_fma_f32 v[208:209], v[160:161], v[218:219], v[208:209]
	v_pk_fma_f32 v[236:237], v[162:163], v[218:219], v[236:237]
	v_pk_fma_f32 v[208:209], v[162:163], v[220:221], v[208:209]
	v_pk_mul_f32 v[238:239], v[234:235], v[236:237]
	v_pk_mul_f32 v[210:211], v[234:235], v[208:209]
	v_exp_f32_e32 v238, v238
	v_exp_f32_e32 v210, v210
	v_exp_f32_e32 v239, v239
	v_exp_f32_e32 v211, v211
	v_pk_add_f32 v[238:239], v[238:239], 1.0 op_sel_hi:[1,0]
	v_pk_add_f32 v[210:211], v[210:211], 1.0 op_sel_hi:[1,0]
	v_rcp_f32_e32 v238, v238
	v_rcp_f32_e32 v210, v210
	v_rcp_f32_e32 v239, v239
	v_rcp_f32_e32 v211, v211
	v_pk_mul_f32 v[236:237], v[236:237], v[238:239]
	v_pk_mul_f32 v[208:209], v[208:209], v[210:211]
	v_cvt_pk_bf16_f32 v83, v236, v237
	v_cvt_pk_bf16_f32 v87, v208, v209
	v_pk_fma_f32 v[236:237], v[156:157], v[216:217], v[154:155]
	v_pk_fma_f32 v[208:209], v[156:157], v[218:219], v[154:155]
	v_pk_fma_f32 v[236:237], v[158:159], v[218:219], v[236:237]
	v_pk_fma_f32 v[208:209], v[158:159], v[220:221], v[208:209]
	v_pk_fma_f32 v[236:237], v[160:161], v[220:221], v[236:237]
	v_pk_fma_f32 v[208:209], v[160:161], v[222:223], v[208:209]
	v_pk_fma_f32 v[236:237], v[162:163], v[222:223], v[236:237]
	v_pk_fma_f32 v[208:209], v[162:163], v[224:225], v[208:209]
	v_pk_mul_f32 v[238:239], v[234:235], v[236:237]
	v_pk_mul_f32 v[210:211], v[234:235], v[208:209]
	v_exp_f32_e32 v238, v238
	v_exp_f32_e32 v210, v210
	v_exp_f32_e32 v239, v239
	v_exp_f32_e32 v211, v211
	v_pk_add_f32 v[238:239], v[238:239], 1.0 op_sel_hi:[1,0]
	v_pk_add_f32 v[210:211], v[210:211], 1.0 op_sel_hi:[1,0]
	v_rcp_f32_e32 v238, v238
	v_rcp_f32_e32 v210, v210
	v_rcp_f32_e32 v239, v239
	v_rcp_f32_e32 v211, v211
	v_pk_mul_f32 v[236:237], v[236:237], v[238:239]
	v_pk_mul_f32 v[208:209], v[208:209], v[210:211]
	v_cvt_pk_bf16_f32 v91, v236, v237
	v_cvt_pk_bf16_f32 v95, v208, v209
	v_pk_fma_f32 v[236:237], v[156:157], v[220:221], v[154:155]
	v_pk_fma_f32 v[208:209], v[156:157], v[222:223], v[154:155]
	v_pk_fma_f32 v[236:237], v[158:159], v[222:223], v[236:237]
	v_pk_fma_f32 v[208:209], v[158:159], v[224:225], v[208:209]
	v_pk_fma_f32 v[236:237], v[160:161], v[224:225], v[236:237]
	v_pk_fma_f32 v[208:209], v[160:161], v[226:227], v[208:209]
	v_pk_fma_f32 v[236:237], v[162:163], v[226:227], v[236:237]
	v_pk_fma_f32 v[208:209], v[162:163], v[228:229], v[208:209]
	v_pk_mul_f32 v[238:239], v[234:235], v[236:237]
	v_pk_mul_f32 v[210:211], v[234:235], v[208:209]
	v_exp_f32_e32 v238, v238
	v_exp_f32_e32 v210, v210
	v_exp_f32_e32 v239, v239
	v_exp_f32_e32 v211, v211
	v_pk_add_f32 v[238:239], v[238:239], 1.0 op_sel_hi:[1,0]
	v_pk_add_f32 v[210:211], v[210:211], 1.0 op_sel_hi:[1,0]
	v_rcp_f32_e32 v238, v238
	v_rcp_f32_e32 v210, v210
	v_rcp_f32_e32 v239, v239
	v_rcp_f32_e32 v211, v211
	v_pk_mul_f32 v[236:237], v[236:237], v[238:239]
	v_pk_mul_f32 v[208:209], v[208:209], v[210:211]
	v_cvt_pk_bf16_f32 v99, v236, v237
	v_cvt_pk_bf16_f32 v103, v208, v209
	v_pk_fma_f32 v[236:237], v[156:157], v[224:225], v[154:155]
	v_pk_fma_f32 v[208:209], v[156:157], v[226:227], v[154:155]
	v_pk_fma_f32 v[236:237], v[158:159], v[226:227], v[236:237]
	v_pk_fma_f32 v[208:209], v[158:159], v[228:229], v[208:209]
	v_pk_fma_f32 v[236:237], v[160:161], v[228:229], v[236:237]
	v_pk_fma_f32 v[208:209], v[160:161], v[230:231], v[208:209]
	v_pk_fma_f32 v[236:237], v[162:163], v[230:231], v[236:237]
	v_pk_fma_f32 v[208:209], v[162:163], v[232:233], v[208:209]
	v_pk_mul_f32 v[238:239], v[234:235], v[236:237]
	v_pk_mul_f32 v[210:211], v[234:235], v[208:209]
	v_exp_f32_e32 v238, v238
	v_exp_f32_e32 v210, v210
	v_exp_f32_e32 v239, v239
	v_exp_f32_e32 v211, v211
	v_pk_add_f32 v[238:239], v[238:239], 1.0 op_sel_hi:[1,0]
	v_pk_add_f32 v[210:211], v[210:211], 1.0 op_sel_hi:[1,0]
	v_rcp_f32_e32 v238, v238
	v_rcp_f32_e32 v210, v210
	v_rcp_f32_e32 v239, v239
	v_rcp_f32_e32 v211, v211
	v_pk_mul_f32 v[236:237], v[236:237], v[238:239]
	v_pk_mul_f32 v[208:209], v[208:209], v[210:211]
	v_cvt_pk_bf16_f32 v107, v236, v237
	v_cvt_pk_bf16_f32 v111, v208, v209
	s_and_saveexec_b64 s[34:35], s[6:7]
	s_cbranch_execz .LBB0_420
	ds_write_b128 v205, v[80:83]
	ds_write_b128 v205, v[84:87] offset:272
	ds_write_b128 v205, v[88:91] offset:544
	ds_write_b128 v205, v[92:95] offset:816
	ds_write_b128 v205, v[96:99] offset:1088
	ds_write_b128 v205, v[100:103] offset:1360
	ds_write_b128 v205, v[104:107] offset:1632
	ds_write_b128 v205, v[108:111] offset:1904

; template <int EPI>
; __device__ __forceinline__ void gemm_epilogue(KP P, f32x4 (&acc)[2][2][4][2], int brow, int bcol, int wr, int wc, int fr_, int fq_, const float* sRu) {
;     ...
;     if (bcol < ZXW) {
;       bfu* zxb = (bfu*)(P->ws + WS_BIG) + (size_t)brow * ZXW + bcol;
; #pragma unroll
;       for (int ai = 0; ai < 2; ++ai)
; #pragma unroll
;         for (int m = 0; m < 4; ++m) {
;           __builtin_amdgcn_sched_barrier(0);
;           unsigned o = (lrow0 + ai * 128 + m * 16) * ZXW + lcol0;
; #pragma unroll
;           for (int bj = 0; bj < 2; ++bj)
; #pragma unroll
;             for (int n = 0; n < 2; ++n) {
;               f32x4 v = acc[ai][bj][m][n];
;               uint2 pk; pk.x = cvt_pk_bf16(v[0], v[1]); pk.y = cvt_pk_bf16(v[2], v[3]);
;               *(uint2*)(zxb + o + bj * 128 + n * 16) = pk;
;             }
;         }
;       const bool has_tail = (brow >= MP) || (((brow + 256) & 4095) == 0);
;       if (has_tail && bcol >= DI) {
; #pragma unroll
;         for (int ai = 0; ai < 2; ++ai)
; #pragma unroll
;           for (int m = 0; m < 4; ++m) {
;             __builtin_amdgcn_sched_barrier(0);
;             int row = brow + lrow0 + ai * 128 + m * 16;
;             float* dst = nullptr;
;             if (row < MP) {
;               int t = row & 4095;
;               if (t >= 4093) dst = P->out + O_CONVP + ((size_t)(row >> 12) * 3 + (t - 4093)) * CONVD;
;             } else {
;               int rs = row - MP, t = rs & 63;
;               if (t >= 61) dst = P->out + O_CONVS + ((size_t)(rs >> 6) * 3 + (t - 61)) * CONVD;
.LBB0_589:
	s_andn2_b64 vcc, exec, s[4:5]
	s_cbranch_vccnz .LBB0_452
	s_lshl_b32 s4, s51, 8
	v_readlane_b32 s2, v241, 20
	s_mul_i32 s5, s18, 0x2800
	s_add_u32 s9, s47, s5
	v_add_u32_e32 v130, s2, v158
	s_mul_hi_i32 s2, s18, 0x2800
	s_addc_u32 s2, s48, s2
	s_ashr_i32 s5, s4, 31
	s_lshl_b64 s[20:21], s[4:5], 1
	s_add_u32 s20, s9, s20
	s_addc_u32 s21, s2, s21
	s_movk_i32 s2, 0x1400
	v_mad_u64_u32 v[132:133], s[70:71], v180, s2, v[130:131]
	v_and_b32_e32 v208, 1, v161
	v_mul_u32_u24_e32 v208, 12, v208
	v_add_u32_e32 v132, v132, v208
	v_mov_b32_e32 v133, v1
	v_lshl_add_u64 v[134:135], v[132:133], 1, s[20:21]
	v_cvt_pk_bf16_f32 v200, v126, v127
	v_cvt_pk_bf16_f32 v201, v128, v129
	v_cvt_pk_bf16_f32 v202, v122, v123
	v_cvt_pk_bf16_f32 v203, v124, v125
	s_nop 1
	v_permlane16_swap_b32_e32 v200, v202
	v_permlane16_swap_b32_e32 v201, v203
	global_store_dwordx4 v[134:135], v[200:203], off
	v_cvt_pk_bf16_f32 v204, v118, v119
	v_cvt_pk_bf16_f32 v205, v120, v121
	v_cvt_pk_bf16_f32 v206, v114, v115
	v_cvt_pk_bf16_f32 v207, v116, v117
	s_nop 1
	v_permlane16_swap_b32_e32 v204, v206
	v_permlane16_swap_b32_e32 v205, v207
	global_store_dwordx4 v[134:135], v[204:207], off offset:256
	v_add_u32_e32 v0, 0x14000, v132
	v_lshl_add_u64 v[134:135], v[0:1], 1, s[20:21]
	v_cvt_pk_bf16_f32 v200, v110, v111
	v_cvt_pk_bf16_f32 v201, v112, v113
	v_cvt_pk_bf16_f32 v202, v106, v107
	v_cvt_pk_bf16_f32 v203, v108, v109
	s_nop 1
	v_permlane16_swap_b32_e32 v200, v202
	v_permlane16_swap_b32_e32 v201, v203
	global_store_dwordx4 v[134:135], v[200:203], off
	v_cvt_pk_bf16_f32 v204, v102, v103
	v_cvt_pk_bf16_f32 v205, v104, v105
	v_cvt_pk_bf16_f32 v206, v98, v99
	v_cvt_pk_bf16_f32 v207, v100, v101
	s_nop 1
	v_permlane16_swap_b32_e32 v204, v206
	v_permlane16_swap_b32_e32 v205, v207
	global_store_dwordx4 v[134:135], v[204:207], off offset:256
	v_add_u32_e32 v0, 0x28000, v132
	v_lshl_add_u64 v[134:135], v[0:1], 1, s[20:21]
	v_cvt_pk_bf16_f32 v200, v94, v95
	v_cvt_pk_bf16_f32 v201, v96, v97
	v_cvt_pk_bf16_f32 v202, v90, v91
	v_cvt_pk_bf16_f32 v203, v92, v93
	s_nop 1
	v_permlane16_swap_b32_e32 v200, v202
	v_permlane16_swap_b32_e32 v201, v203
	global_store_dwordx4 v[134:135], v[200:203], off
	v_cvt_pk_bf16_f32 v204, v86, v87
	v_cvt_pk_bf16_f32 v205, v88, v89
	v_cvt_pk_bf16_f32 v206, v82, v83
	v_cvt_pk_bf16_f32 v207, v84, v85
	s_nop 1
	v_permlane16_swap_b32_e32 v204, v206
	v_permlane16_swap_b32_e32 v205, v207
	global_store_dwordx4 v[134:135], v[204:207], off offset:256
	v_add_u32_e32 v0, 0x3c000, v132
	v_lshl_add_u64 v[134:135], v[0:1], 1, s[20:21]
	v_cvt_pk_bf16_f32 v200, v78, v79
	v_cvt_pk_bf16_f32 v201, v80, v81
	v_cvt_pk_bf16_f32 v202, v74, v75
	v_cvt_pk_bf16_f32 v203, v76, v77
	s_nop 1
	v_permlane16_swap_b32_e32 v200, v202
	v_permlane16_swap_b32_e32 v201, v203
	global_store_dwordx4 v[134:135], v[200:203], off
	v_cvt_pk_bf16_f32 v204, v70, v71
	v_cvt_pk_bf16_f32 v205, v72, v73
	v_cvt_pk_bf16_f32 v206, v66, v67
	v_cvt_pk_bf16_f32 v207, v68, v69
	s_nop 1
	v_permlane16_swap_b32_e32 v204, v206
	v_permlane16_swap_b32_e32 v205, v207
	global_store_dwordx4 v[134:135], v[204:207], off offset:256
	v_add_u32_e32 v0, 0xa0000, v132
	v_lshl_add_u64 v[134:135], v[0:1], 1, s[20:21]
	v_cvt_pk_bf16_f32 v200, v62, v63
	v_cvt_pk_bf16_f32 v201, v64, v65
	v_cvt_pk_bf16_f32 v202, v58, v59
	v_cvt_pk_bf16_f32 v203, v60, v61
	s_nop 1
	v_permlane16_swap_b32_e32 v200, v202
	v_permlane16_swap_b32_e32 v201, v203
	global_store_dwordx4 v[134:135], v[200:203], off
	v_cvt_pk_bf16_f32 v204, v54, v55
	v_cvt_pk_bf16_f32 v205, v56, v57
	v_cvt_pk_bf16_f32 v206, v50, v51
	v_cvt_pk_bf16_f32 v207, v52, v53
	s_nop 1
	v_permlane16_swap_b32_e32 v204, v206
	v_permlane16_swap_b32_e32 v205, v207
	global_store_dwordx4 v[134:135], v[204:207], off offset:256
	v_add_u32_e32 v0, 0xb4000, v132
	v_lshl_add_u64 v[134:135], v[0:1], 1, s[20:21]
	v_cvt_pk_bf16_f32 v200, v46, v47
	v_cvt_pk_bf16_f32 v201, v48, v49
	v_cvt_pk_bf16_f32 v202, v42, v43
	v_cvt_pk_bf16_f32 v203, v44, v45
	s_nop 1
	v_permlane16_swap_b32_e32 v200, v202
	v_permlane16_swap_b32_e32 v201, v203
	global_store_dwordx4 v[134:135], v[200:203], off
	v_cvt_pk_bf16_f32 v204, v38, v39
	v_cvt_pk_bf16_f32 v205, v40, v41
	v_cvt_pk_bf16_f32 v206, v34, v35
	v_cvt_pk_bf16_f32 v207, v36, v37
	s_nop 1
	v_permlane16_swap_b32_e32 v204, v206
	v_permlane16_swap_b32_e32 v205, v207
	global_store_dwordx4 v[134:135], v[204:207], off offset:256
	v_add_u32_e32 v0, 0xc8000, v132
	v_lshl_add_u64 v[134:135], v[0:1], 1, s[20:21]
	v_cvt_pk_bf16_f32 v200, v30, v31
	v_cvt_pk_bf16_f32 v201, v32, v33
	v_cvt_pk_bf16_f32 v202, v26, v27
	v_cvt_pk_bf16_f32 v203, v28, v29
	s_nop 1
	v_permlane16_swap_b32_e32 v200, v202
	v_permlane16_swap_b32_e32 v201, v203
	global_store_dwordx4 v[134:135], v[200:203], off
	v_cvt_pk_bf16_f32 v204, v22, v23
	v_cvt_pk_bf16_f32 v205, v24, v25
	v_cvt_pk_bf16_f32 v206, v18, v19
	v_cvt_pk_bf16_f32 v207, v20, v21
	s_nop 1
	v_permlane16_swap_b32_e32 v204, v206
	v_permlane16_swap_b32_e32 v205, v207
	global_store_dwordx4 v[134:135], v[204:207], off offset:256
	v_add_u32_e32 v0, 0xdc000, v132
	s_cmpk_lt_i32 s60, 0x100
	v_lshl_add_u64 v[132:133], v[0:1], 1, s[20:21]
	s_cselect_b64 s[20:21], -1, 0
	s_and_b32 s2, s60, 15
	s_cmp_lg_u32 s2, 15
	s_cselect_b64 s[70:71], -1, 0
	s_and_b64 s[20:21], s[20:21], s[70:71]
	s_cmp_lt_i32 s51, 8
	v_cvt_pk_bf16_f32 v200, v14, v15
	v_cvt_pk_bf16_f32 v201, v16, v17
	s_cselect_b64 s[70:71], -1, 0
	v_cvt_pk_bf16_f32 v202, v10, v11
	v_cvt_pk_bf16_f32 v203, v12, v13
	s_or_b64 s[20:21], s[70:71], s[20:21]
	s_nop 1
	v_permlane16_swap_b32_e32 v200, v202
	v_permlane16_swap_b32_e32 v201, v203
	global_store_dwordx4 v[132:133], v[200:203], off
	v_cvt_pk_bf16_f32 v204, v6, v7
	v_cvt_pk_bf16_f32 v205, v8, v9
	s_and_b64 vcc, exec, s[20:21]
	v_cvt_pk_bf16_f32 v206, v2, v3
	v_cvt_pk_bf16_f32 v207, v4, v5
	s_nop 1
	v_permlane16_swap_b32_e32 v204, v206
	v_permlane16_swap_b32_e32 v205, v207
	global_store_dwordx4 v[132:133], v[204:207], off offset:256
	s_cbranch_vccnz .LBB0_452
	v_add_u32_e32 v131, s18, v180
	v_and_b32_e32 v134, 63, v179
	s_mov_b32 s15, 0xffff
	v_cmp_lt_i32_e32 vcc, s15, v131
	s_and_saveexec_b64 s[18:19], vcc
	s_xor_b64 s[18:19], exec, s[18:19]
	s_movk_i32 s9, 0x3000
	s_movk_i32 s51, 0xffc
	s_cbranch_execz .LBB0_595
	v_cmp_lt_u32_e32 vcc, 60, v134
	v_mov_b64_e32 v[132:133], 0
	s_and_saveexec_b64 s[20:21], vcc
	s_cbranch_execz .LBB0_594
	s_load_dwordx2 s[70:71], s[0:1], 0xd8
	v_add_u32_e32 v0, 0xffff0000, v131
	v_lshrrev_b32_e32 v0, 6, v0
	v_lshl_add_u32 v0, v0, 1, v0
	s_movk_i32 s2, 0xffc3
	v_add3_u32 v0, v134, v0, s2
	s_waitcnt lgkmcnt(0)
	v_mov_b64_e32 v[132:133], s[70:71]
	v_mad_u64_u32 v[132:133], s[70:71], v0, s9, v[132:133]
	s_mov_b64 s[70:71], 0x31290000
	s_nop 0
	v_lshl_add_u64 v[132:133], v[132:133], 0, s[70:71]
